# P5: batched LDS staging loads + C_prev.q/n.q stage unrolled with static register indexing (removes select chains); P0: adaLN tile loads batched
# speedup vs baseline: 1.0380x; 1.0380x over previous
; __device__ __forceinline__ unsigned f2bf(float f) { unsigned u = __builtin_bit_cast(unsigned, f); return (u + 0x7fffu + ((u >> 16) & 1u)) >> 16; }
; #define LDS_WAIT() asm volatile("s_waitcnt lgkmcnt(0)" ::: "memory")
; __device__ __forceinline__ void phase0(const Args& a, LAS unsigned char* lds, int tid, int wave, int lane, int vcu, int G, int pmask) {
;     ...
;             for (int ch = 0; ch < 2; ++ch) {
;                 const int k0 = 128 * wave + 64 * ch;
; #pragma unroll 8
;                 for (int i = 0; i < 32; ++i) { const int kk = 2 * i + (lane >> 5); scr[kk * 33 + (lane & 31)] = wada[(size_t)(k0 + kk) * 6144 + n0 + (lane & 31)]; }
;                 LDS_WAIT(); asm volatile("" ::: "memory");
; #pragma unroll
;                 for (int ks = 0; ks < 2; ++ks) {
;                     bf16x8 ah[2], al[2];
; #pragma unroll
;                     for (int nt = 0; nt < 2; ++nt) { float v[8]; unsigned hb[8], lb[8];
; #pragma unroll
;                         for (int j = 0; j < 8; ++j) { v[j] = scr[(32 * ks + 8 * g + j) * 33 + 16 * nt + i16]; hb[j] = f2bf(v[j]); lb[j] = f2bf(v[j] - __uint_as_float(hb[j] << 16)); }
;                         u32x4 wh, wl; wh.x = hb[0] | (hb[1] << 16); wh.y = hb[2] | (hb[3] << 16); wh.z = hb[4] | (hb[5] << 16); wh.w = hb[6] | (hb[7] << 16);
;                         wl.x = lb[0] | (lb[1] << 16); wl.y = lb[2] | (lb[3] << 16); wl.z = lb[4] | (lb[5] << 16); wl.w = lb[6] | (lb[7] << 16);
;                         ah[nt] = __builtin_bit_cast(bf16x8, wh); al[nt] = __builtin_bit_cast(bf16x8, wl); }
.LBB0_14:
	s_xor_b64 s[54:55], s[56:57], -1
	s_or_b32 s56, s82, s33
	v_or_b32_e32 v75, s56, v1
	v_or_b32_e32 v74, s56, v110
	v_mad_u64_u32 v[76:77], s[86:87], v74, s58, v[144:145]
	v_mad_u32_u24 v78, v110, s59, v116
	s_mov_b64 s[84:85], 0xc000
	global_load_dword v184, v[76:77], off
	v_lshl_add_u64 v[76:77], v[76:77], 0, s[84:85]
	global_load_dword v185, v[76:77], off
	v_lshl_add_u64 v[76:77], v[76:77], 0, s[84:85]
	global_load_dword v186, v[76:77], off
	v_lshl_add_u64 v[76:77], v[76:77], 0, s[84:85]
	global_load_dword v187, v[76:77], off
	v_lshl_add_u64 v[76:77], v[76:77], 0, s[84:85]
	global_load_dword v188, v[76:77], off
	v_lshl_add_u64 v[76:77], v[76:77], 0, s[84:85]
	global_load_dword v189, v[76:77], off
	v_lshl_add_u64 v[76:77], v[76:77], 0, s[84:85]
	global_load_dword v190, v[76:77], off
	v_lshl_add_u64 v[76:77], v[76:77], 0, s[84:85]
	global_load_dword v191, v[76:77], off
	v_lshl_add_u64 v[76:77], v[76:77], 0, s[84:85]
	global_load_dword v192, v[76:77], off
	v_lshl_add_u64 v[76:77], v[76:77], 0, s[84:85]
	global_load_dword v193, v[76:77], off
	v_lshl_add_u64 v[76:77], v[76:77], 0, s[84:85]
	global_load_dword v194, v[76:77], off
	v_lshl_add_u64 v[76:77], v[76:77], 0, s[84:85]
	global_load_dword v195, v[76:77], off
	v_lshl_add_u64 v[76:77], v[76:77], 0, s[84:85]
	global_load_dword v196, v[76:77], off
	v_lshl_add_u64 v[76:77], v[76:77], 0, s[84:85]
	global_load_dword v197, v[76:77], off
	v_lshl_add_u64 v[76:77], v[76:77], 0, s[84:85]
	global_load_dword v198, v[76:77], off
	v_lshl_add_u64 v[76:77], v[76:77], 0, s[84:85]
	global_load_dword v199, v[76:77], off
	v_lshl_add_u64 v[76:77], v[76:77], 0, s[84:85]
	global_load_dword v200, v[76:77], off
	v_lshl_add_u64 v[76:77], v[76:77], 0, s[84:85]
	global_load_dword v201, v[76:77], off
	v_lshl_add_u64 v[76:77], v[76:77], 0, s[84:85]
	global_load_dword v202, v[76:77], off
	v_lshl_add_u64 v[76:77], v[76:77], 0, s[84:85]
	global_load_dword v203, v[76:77], off
	v_lshl_add_u64 v[76:77], v[76:77], 0, s[84:85]
	global_load_dword v204, v[76:77], off
	v_lshl_add_u64 v[76:77], v[76:77], 0, s[84:85]
	global_load_dword v205, v[76:77], off
	v_lshl_add_u64 v[76:77], v[76:77], 0, s[84:85]
	global_load_dword v206, v[76:77], off
	v_lshl_add_u64 v[76:77], v[76:77], 0, s[84:85]
	global_load_dword v207, v[76:77], off
	v_lshl_add_u64 v[76:77], v[76:77], 0, s[84:85]
	global_load_dword v208, v[76:77], off
	v_lshl_add_u64 v[76:77], v[76:77], 0, s[84:85]
	global_load_dword v209, v[76:77], off
	v_lshl_add_u64 v[76:77], v[76:77], 0, s[84:85]
	global_load_dword v210, v[76:77], off
	v_lshl_add_u64 v[76:77], v[76:77], 0, s[84:85]
	global_load_dword v211, v[76:77], off
	v_lshl_add_u64 v[76:77], v[76:77], 0, s[84:85]
	global_load_dword v212, v[76:77], off
	v_lshl_add_u64 v[76:77], v[76:77], 0, s[84:85]
	global_load_dword v213, v[76:77], off
	v_lshl_add_u64 v[76:77], v[76:77], 0, s[84:85]
	global_load_dword v214, v[76:77], off
	v_lshl_add_u64 v[76:77], v[76:77], 0, s[84:85]
	global_load_dword v215, v[76:77], off
	s_waitcnt vmcnt(31)
	ds_write_b32 v78, v184
	s_waitcnt vmcnt(30)
	ds_write_b32 v78, v185 offset:264
	s_waitcnt vmcnt(29)
	ds_write_b32 v78, v186 offset:528
	s_waitcnt vmcnt(28)
	ds_write_b32 v78, v187 offset:792
	s_waitcnt vmcnt(27)
	ds_write_b32 v78, v188 offset:1056
	s_waitcnt vmcnt(26)
	ds_write_b32 v78, v189 offset:1320
	s_waitcnt vmcnt(25)
	ds_write_b32 v78, v190 offset:1584
	s_waitcnt vmcnt(24)
	ds_write_b32 v78, v191 offset:1848
	s_waitcnt vmcnt(23)
	ds_write_b32 v78, v192 offset:2112
	s_waitcnt vmcnt(22)
	ds_write_b32 v78, v193 offset:2376
	s_waitcnt vmcnt(21)
	ds_write_b32 v78, v194 offset:2640
	s_waitcnt vmcnt(20)
	ds_write_b32 v78, v195 offset:2904
	s_waitcnt vmcnt(19)
	ds_write_b32 v78, v196 offset:3168
	s_waitcnt vmcnt(18)
	ds_write_b32 v78, v197 offset:3432
	s_waitcnt vmcnt(17)
	ds_write_b32 v78, v198 offset:3696
	s_waitcnt vmcnt(16)
	ds_write_b32 v78, v199 offset:3960
	s_waitcnt vmcnt(15)
	ds_write_b32 v78, v200 offset:4224
	s_waitcnt vmcnt(14)
	ds_write_b32 v78, v201 offset:4488
	s_waitcnt vmcnt(13)
	ds_write_b32 v78, v202 offset:4752
	s_waitcnt vmcnt(12)
	ds_write_b32 v78, v203 offset:5016
	s_waitcnt vmcnt(11)
	ds_write_b32 v78, v204 offset:5280
	s_waitcnt vmcnt(10)
	ds_write_b32 v78, v205 offset:5544
	s_waitcnt vmcnt(9)
	ds_write_b32 v78, v206 offset:5808
	s_waitcnt vmcnt(8)
	ds_write_b32 v78, v207 offset:6072
	s_waitcnt vmcnt(7)
	ds_write_b32 v78, v208 offset:6336
	s_waitcnt vmcnt(6)
	ds_write_b32 v78, v209 offset:6600
	s_waitcnt vmcnt(5)
	ds_write_b32 v78, v210 offset:6864
	s_waitcnt vmcnt(4)
	ds_write_b32 v78, v211 offset:7128
	s_waitcnt vmcnt(3)
	ds_write_b32 v78, v212 offset:7392
	s_waitcnt vmcnt(2)
	ds_write_b32 v78, v213 offset:7656
	s_waitcnt vmcnt(1)
	ds_write_b32 v78, v214 offset:7920
	s_waitcnt vmcnt(0)
	ds_write_b32 v78, v215 offset:8184
	s_waitcnt lgkmcnt(0)
	ds_read2_b32 v[74:75], v169 offset1:16
	ds_read2_b32 v[84:85], v169 offset0:33 offset1:49
	ds_read2_b32 v[86:87], v169 offset0:66 offset1:82
	ds_read2_b32 v[92:93], v169 offset0:99 offset1:115
	ds_read2_b32 v[98:99], v169 offset0:132 offset1:148
	ds_read2_b32 v[100:101], v169 offset0:165 offset1:181
	ds_read2_b32 v[102:103], v169 offset0:198 offset1:214
	ds_read2_b32 v[104:105], v169 offset0:231 offset1:247
	s_waitcnt lgkmcnt(5)
	v_and_b32_sdwa v78, v86, v170 dst_sel:DWORD dst_unused:UNUSED_PAD src0_sel:WORD_1 src1_sel:DWORD
	v_and_b32_sdwa v79, v74, v170 dst_sel:DWORD dst_unused:UNUSED_PAD src0_sel:WORD_1 src1_sel:DWORD
	v_mov_b32_e32 v76, v74
	v_mov_b32_e32 v77, v86
	v_add3_u32 v86, v86, v78, s76
	v_add3_u32 v74, v74, v79, s76
	v_and_b32_e32 v79, 0xffff0000, v86
	v_and_b32_e32 v78, 0xffff0000, v74
	v_pk_add_f32 v[80:81], v[76:77], v[78:79] neg_lo:[0,1] neg_hi:[0,1]
	s_waitcnt lgkmcnt(4)
; __device__ __forceinline__ unsigned f2bf(float f) { unsigned u = __builtin_bit_cast(unsigned, f); return (u + 0x7fffu + ((u >> 16) & 1u)) >> 16; }
; __device__ __forceinline__ void phase0(const Args& a, LAS unsigned char* lds, int tid, int wave, int lane, int vcu, int G, int pmask) {
;     ...
;                     for (int nt = 0; nt < 2; ++nt) { float v[8]; unsigned hb[8], lb[8];
; #pragma unroll
;                         for (int j = 0; j < 8; ++j) { v[j] = scr[(32 * ks + 8 * g + j) * 33 + 16 * nt + i16]; hb[j] = f2bf(v[j]); lb[j] = f2bf(v[j] - __uint_as_float(hb[j] << 16)); }
;                         u32x4 wh, wl; wh.x = hb[0] | (hb[1] << 16); wh.y = hb[2] | (hb[3] << 16); wh.z = hb[4] | (hb[5] << 16); wh.w = hb[6] | (hb[7] << 16);
;                         wl.x = lb[0] | (lb[1] << 16); wl.y = lb[2] | (lb[3] << 16); wl.z = lb[4] | (lb[5] << 16); wl.w = lb[6] | (lb[7] << 16);
;                         ah[nt] = __builtin_bit_cast(bf16x8, wh); al[nt] = __builtin_bit_cast(bf16x8, wl); }
; #pragma unroll
;                     for (int bt = 0; bt < 9; ++bt) {
;                         const int b = 16 * bt + i16; const int k = k0 + 32 * ks + 8 * g;
;                         f32x4 c0 = {0.f, 0.f, 0.f, 0.f}, c1 = c0;
;                         if (b < 129) { const float* cr = b == 0 ? cp + k : cs + (size_t)(b - 1) * DM + k; c0 = *(const f32x4*)cr; c1 = *(const f32x4*)(cr + 4); }
	v_and_b32_sdwa v78, v92, v170 dst_sel:DWORD dst_unused:UNUSED_PAD src0_sel:WORD_1 src1_sel:DWORD
	v_and_b32_sdwa v79, v84, v170 dst_sel:DWORD dst_unused:UNUSED_PAD src0_sel:WORD_1 src1_sel:DWORD
	v_add3_u32 v78, v92, v78, s76
	v_add3_u32 v82, v84, v79, s76
	v_mov_b32_e32 v76, v84
	v_mov_b32_e32 v77, v92
	v_and_b32_e32 v79, 0xffff0000, v78
	v_and_b32_e32 v78, 0xffff0000, v82
	v_pk_add_f32 v[82:83], v[76:77], v[78:79] neg_lo:[0,1] neg_hi:[0,1]
	v_or_b32_sdwa v76, v78, v74 dst_sel:DWORD dst_unused:UNUSED_PAD src0_sel:DWORD src1_sel:WORD_1
	s_waitcnt lgkmcnt(1)
	v_and_b32_sdwa v74, v102, v170 dst_sel:DWORD dst_unused:UNUSED_PAD src0_sel:WORD_1 src1_sel:DWORD
	v_and_b32_sdwa v84, v98, v170 dst_sel:DWORD dst_unused:UNUSED_PAD src0_sel:WORD_1 src1_sel:DWORD
	s_load_dwordx16 s[60:75], s[0:1], 0x0
	v_add3_u32 v74, v102, v74, s76
	v_add3_u32 v84, v98, v84, s76
	v_or_b32_e32 v112, s56, v117
	v_or_b32_sdwa v77, v79, v86 dst_sel:DWORD dst_unused:UNUSED_PAD src0_sel:DWORD src1_sel:WORD_1
	v_mov_b32_e32 v78, v98
	v_mov_b32_e32 v79, v102
	v_and_b32_e32 v89, 0xffff0000, v74
	v_and_b32_e32 v88, 0xffff0000, v84
	v_pk_add_f32 v[106:107], v[78:79], v[88:89] neg_lo:[0,1] neg_hi:[0,1]
	v_lshlrev_b64 v[78:79], 2, v[112:113]
	v_lshl_add_u64 v[146:147], s[8:9], 0, v[78:79]
	s_waitcnt lgkmcnt(0)
	v_lshl_add_u64 v[108:109], s[74:75], 0, v[78:79]
	v_lshl_add_u64 v[158:159], v[146:147], 0, v[120:121]
	v_cndmask_b32_e64 v79, v159, v109, s[2:3]
	v_cndmask_b32_e64 v78, v158, v108, s[2:3]
	global_load_dwordx4 v[94:97], v[78:79], off offset:16
	global_load_dwordx4 v[88:91], v[78:79], off
	v_and_b32_sdwa v86, v104, v170 dst_sel:DWORD dst_unused:UNUSED_PAD src0_sel:WORD_1 src1_sel:DWORD
	v_and_b32_sdwa v92, v100, v170 dst_sel:DWORD dst_unused:UNUSED_PAD src0_sel:WORD_1 src1_sel:DWORD
	v_add3_u32 v86, v104, v86, s76
	v_add3_u32 v92, v100, v92, s76
	v_mov_b32_e32 v78, v100
	v_mov_b32_e32 v79, v104
	v_and_b32_e32 v149, 0xffff0000, v86
	v_and_b32_e32 v148, 0xffff0000, v92
	v_pk_add_f32 v[150:151], v[78:79], v[148:149] neg_lo:[0,1] neg_hi:[0,1]
	v_or_b32_sdwa v78, v148, v84 dst_sel:DWORD dst_unused:UNUSED_PAD src0_sel:DWORD src1_sel:WORD_1
	v_bfe_u32 v84, v150, 16, 1
	v_bfe_u32 v86, v83, 16, 1
	v_bfe_u32 v92, v82, 16, 1
	v_bfe_u32 v98, v106, 16, 1
	v_bfe_u32 v100, v107, 16, 1
	v_or_b32_sdwa v79, v149, v74 dst_sel:DWORD dst_unused:UNUSED_PAD src0_sel:DWORD src1_sel:WORD_1
	v_bfe_u32 v74, v151, 16, 1
	v_add3_u32 v92, v82, v92, s76
	v_add3_u32 v86, v83, v86, s76
	v_add3_u32 v82, v150, v84, s76
	v_bfe_u32 v83, v80, 16, 1
	v_bfe_u32 v84, v81, 16, 1
	v_add3_u32 v100, v107, v100, s76
	v_add3_u32 v98, v106, v98, s76
	v_add3_u32 v74, v151, v74, s76
	v_add3_u32 v81, v81, v84, s76
	v_add3_u32 v80, v80, v83, s76
	v_lshrrev_b32_e32 v84, 16, v98
	v_lshrrev_b32_e32 v83, 16, v100
	v_and_or_b32 v83, v74, s77, v83
	v_and_or_b32 v82, v82, s77, v84
	v_and_b32_sdwa v74, v87, v170 dst_sel:DWORD dst_unused:UNUSED_PAD src0_sel:WORD_1 src1_sel:DWORD
	v_and_b32_sdwa v84, v75, v170 dst_sel:DWORD dst_unused:UNUSED_PAD src0_sel:WORD_1 src1_sel:DWORD
	v_lshrrev_b32_e32 v81, 16, v81
	v_add3_u32 v98, v87, v74, s76
	v_add3_u32 v84, v75, v84, s76
	v_and_or_b32 v81, v86, s77, v81
	v_mov_b32_e32 v86, v75
	v_and_b32_e32 v75, 0xffff0000, v98
	v_and_b32_e32 v74, 0xffff0000, v84
	v_lshrrev_b32_e32 v80, 16, v80
	v_pk_add_f32 v[106:107], v[86:87], v[74:75] neg_lo:[0,1] neg_hi:[0,1]
	v_and_b32_sdwa v74, v93, v170 dst_sel:DWORD dst_unused:UNUSED_PAD src0_sel:WORD_1 src1_sel:DWORD
	v_and_b32_sdwa v75, v85, v170 dst_sel:DWORD dst_unused:UNUSED_PAD src0_sel:WORD_1 src1_sel:DWORD
	v_and_or_b32 v80, v92, s77, v80
	v_mov_b32_e32 v92, v85
	v_add3_u32 v74, v93, v74, s76
	v_add3_u32 v85, v85, v75, s76
	v_and_b32_e32 v75, 0xffff0000, v74
	v_and_b32_e32 v74, 0xffff0000, v85
	v_pk_add_f32 v[92:93], v[92:93], v[74:75] neg_lo:[0,1] neg_hi:[0,1]
	v_or_b32_sdwa v84, v74, v84 dst_sel:DWORD dst_unused:UNUSED_PAD src0_sel:DWORD src1_sel:WORD_1
	v_or_b32_sdwa v85, v75, v98 dst_sel:DWORD dst_unused:UNUSED_PAD src0_sel:DWORD src1_sel:WORD_1
	v_and_b32_sdwa v74, v103, v170 dst_sel:DWORD dst_unused:UNUSED_PAD src0_sel:WORD_1 src1_sel:DWORD
	v_and_b32_sdwa v75, v99, v170 dst_sel:DWORD dst_unused:UNUSED_PAD src0_sel:WORD_1 src1_sel:DWORD
	v_add3_u32 v87, v103, v74, s76
	v_add3_u32 v86, v99, v75, s76
	v_mov_b32_e32 v102, v99
	v_and_b32_e32 v75, 0xffff0000, v87
	v_and_b32_e32 v74, 0xffff0000, v86
	v_pk_add_f32 v[98:99], v[102:103], v[74:75] neg_lo:[0,1] neg_hi:[0,1]
	v_and_b32_sdwa v74, v105, v170 dst_sel:DWORD dst_unused:UNUSED_PAD src0_sel:WORD_1 src1_sel:DWORD
	v_and_b32_sdwa v75, v101, v170 dst_sel:DWORD dst_unused:UNUSED_PAD src0_sel:WORD_1 src1_sel:DWORD
	v_add3_u32 v74, v105, v74, s76
	v_add3_u32 v100, v101, v75, s76
	v_mov_b32_e32 v104, v101
	v_and_b32_e32 v75, 0xffff0000, v74
	v_and_b32_e32 v74, 0xffff0000, v100
	v_pk_add_f32 v[100:101], v[104:105], v[74:75] neg_lo:[0,1] neg_hi:[0,1]
	v_or_b32_sdwa v87, v75, v87 dst_sel:DWORD dst_unused:UNUSED_PAD src0_sel:DWORD src1_sel:WORD_1
	v_bfe_u32 v75, v93, 16, 1
	v_or_b32_sdwa v86, v74, v86 dst_sel:DWORD dst_unused:UNUSED_PAD src0_sel:DWORD src1_sel:WORD_1
	v_bfe_u32 v103, v100, 16, 1
	v_bfe_u32 v74, v92, 16, 1
	v_add3_u32 v75, v93, v75, s76
	v_bfe_u32 v102, v101, 16, 1
	v_add3_u32 v74, v92, v74, s76
	v_add3_u32 v112, v100, v103, s76
	v_add3_u32 v129, v101, v102, s76
	s_waitcnt vmcnt(0)
; __device__ __forceinline__ unsigned f2bf(float f) { unsigned u = __builtin_bit_cast(unsigned, f); return (u + 0x7fffu + ((u >> 16) & 1u)) >> 16; }
; __device__ __forceinline__ f32x4 mfma16(bf16x8 a, bf16x8 b, f32x4 c) { return __builtin_amdgcn_mfma_f32_16x16x32_bf16(a, b, c, 0, 0, 0); }
; __device__ __forceinline__ void phase0(const Args& a, LAS unsigned char* lds, int tid, int wave, int lane, int vcu, int G, int pmask) {
;     ...
;                     for (int bt = 0; bt < 9; ++bt) {
;                         const int b = 16 * bt + i16; const int k = k0 + 32 * ks + 8 * g;
;                         f32x4 c0 = {0.f, 0.f, 0.f, 0.f}, c1 = c0;
;                         if (b < 129) { const float* cr = b == 0 ? cp + k : cs + (size_t)(b - 1) * DM + k; c0 = *(const f32x4*)cr; c1 = *(const f32x4*)(cr + 4); }
;                         unsigned hb[8], lb[8];
; #pragma unroll
;                         for (int j = 0; j < 8; ++j) { const float c = j < 4 ? c0[j & 3] : c1[j & 3]; const float sv = c * __builtin_amdgcn_rcpf(1.f + __expf(-c)); hb[j] = f2bf(sv); lb[j] = f2bf(sv - __uint_as_float(hb[j] << 16)); }
;                         u32x4 wh, wl; wh.x = hb[0] | (hb[1] << 16); wh.y = hb[2] | (hb[3] << 16); wh.z = hb[4] | (hb[5] << 16); wh.w = hb[6] | (hb[7] << 16);
;                         wl.x = lb[0] | (lb[1] << 16); wl.y = lb[2] | (lb[3] << 16); wl.z = lb[4] | (lb[5] << 16); wl.w = lb[6] | (lb[7] << 16);
;                         const bf16x8 bh = __builtin_bit_cast(bf16x8, wh), bl = __builtin_bit_cast(bf16x8, wl);
; #pragma unroll
;                         for (int nt = 0; nt < 2; ++nt) { acc[nt][bt] = mfma16(ah[nt], bh, acc[nt][bt]); acc[nt][bt] = mfma16(ah[nt], bl, acc[nt][bt]); acc[nt][bt] = mfma16(al[nt], bh, acc[nt][bt]); }
	v_mul_f32_e32 v93, 0xbfb8aa3b, v89
	v_mul_f32_e32 v92, 0xbfb8aa3b, v88
	v_exp_f32_e32 v93, v93
	v_mul_f32_e32 v100, 0xbfb8aa3b, v90
	v_exp_f32_e32 v92, v92
	v_exp_f32_e32 v101, v100
	v_mul_f32_e32 v100, 0xbfb8aa3b, v91
	v_exp_f32_e32 v102, v100
	v_add_f32_e32 v93, 1.0, v93
	v_add_f32_e32 v92, 1.0, v92
	v_rcp_f32_e32 v100, v93
	v_add_f32_e32 v93, 1.0, v101
	v_rcp_f32_e32 v92, v92
	v_rcp_f32_e32 v93, v93
	v_add_f32_e32 v101, 1.0, v102
	v_mul_f32_e32 v102, 0xbfb8aa3b, v94
	v_mul_f32_e32 v103, 0xbfb8aa3b, v96
	v_exp_f32_e32 v102, v102
	v_exp_f32_e32 v103, v103
	v_rcp_f32_e32 v101, v101
	v_mov_b32_e32 v104, v88
	v_mov_b32_e32 v105, v90
	v_pk_mul_f32 v[148:149], v[104:105], v[92:93]
	v_add_f32_e32 v102, 1.0, v102
	v_and_b32_sdwa v88, v149, v170 dst_sel:DWORD dst_unused:UNUSED_PAD src0_sel:WORD_1 src1_sel:DWORD
	v_and_b32_sdwa v90, v148, v170 dst_sel:DWORD dst_unused:UNUSED_PAD src0_sel:WORD_1 src1_sel:DWORD
	v_add_f32_e32 v103, 1.0, v103
	v_add3_u32 v133, v149, v88, s76
	v_add3_u32 v135, v148, v90, s76
	v_mov_b32_e32 v90, v89
	v_rcp_f32_e32 v102, v102
	v_rcp_f32_e32 v103, v103
	v_and_b32_e32 v149, 0xffff0000, v133
	v_and_b32_e32 v148, 0xffff0000, v135
	v_pk_mul_f32 v[88:89], v[90:91], v[100:101]
	v_pk_fma_f32 v[104:105], v[104:105], v[92:93], v[148:149] neg_lo:[0,0,1] neg_hi:[0,0,1]
	v_and_b32_sdwa v92, v89, v170 dst_sel:DWORD dst_unused:UNUSED_PAD src0_sel:WORD_1 src1_sel:DWORD
	v_and_b32_sdwa v93, v88, v170 dst_sel:DWORD dst_unused:UNUSED_PAD src0_sel:WORD_1 src1_sel:DWORD
	v_add3_u32 v89, v89, v92, s76
	v_add3_u32 v88, v88, v93, s76
	v_and_b32_e32 v93, 0xffff0000, v89
	v_and_b32_e32 v92, 0xffff0000, v88
	v_mov_b32_e32 v88, v94
	v_mov_b32_e32 v89, v96
	v_pk_fma_f32 v[90:91], v[90:91], v[100:101], v[92:93] neg_lo:[0,0,1] neg_hi:[0,0,1]
	v_pk_mul_f32 v[100:101], v[88:89], v[102:103]
	v_lshl_add_u64 v[148:149], v[146:147], 0, v[122:123]
	v_and_b32_sdwa v94, v101, v170 dst_sel:DWORD dst_unused:UNUSED_PAD src0_sel:WORD_1 src1_sel:DWORD
	v_and_b32_sdwa v96, v100, v170 dst_sel:DWORD dst_unused:UNUSED_PAD src0_sel:WORD_1 src1_sel:DWORD
	v_add3_u32 v137, v101, v94, s76
	v_add3_u32 v139, v100, v96, s76
	v_and_b32_e32 v101, 0xffff0000, v137
	v_and_b32_e32 v100, 0xffff0000, v139
	v_pk_fma_f32 v[100:101], v[88:89], v[102:103], v[100:101] neg_lo:[0,0,1] neg_hi:[0,0,1]
	v_bfe_u32 v89, v98, 16, 1
	v_bfe_u32 v94, v99, 16, 1
	v_add3_u32 v143, v98, v89, s76
	v_mul_f32_e32 v89, 0xbfb8aa3b, v95
	v_add3_u32 v141, v99, v94, s76
	v_exp_f32_e32 v94, v89
	v_mul_f32_e32 v89, 0xbfb8aa3b, v97
	v_exp_f32_e32 v96, v89
	v_bfe_u32 v103, v90, 16, 1
	v_add_f32_e32 v94, 1.0, v94
	v_rcp_f32_e32 v98, v94
	v_add_f32_e32 v94, 1.0, v96
	v_rcp_f32_e32 v99, v94
	v_mov_b32_e32 v96, v95
	s_mov_b32 s56, 0xf000
	v_add3_u32 v90, v90, v103, s76
	v_pk_mul_f32 v[94:95], v[96:97], v[98:99]
	v_bfe_u32 v103, v101, 16, 1
	v_and_b32_sdwa v102, v95, v170 dst_sel:DWORD dst_unused:UNUSED_PAD src0_sel:WORD_1 src1_sel:DWORD
	v_add3_u32 v95, v95, v102, s76
	v_and_b32_sdwa v102, v94, v170 dst_sel:DWORD dst_unused:UNUSED_PAD src0_sel:WORD_1 src1_sel:DWORD
	v_add3_u32 v94, v94, v102, s76
	v_and_b32_e32 v95, 0xffff0000, v95
	v_and_b32_e32 v94, 0xffff0000, v94
	v_pk_fma_f32 v[96:97], v[96:97], v[98:99], v[94:95] neg_lo:[0,0,1] neg_hi:[0,0,1]
	v_bfe_u32 v102, v91, 16, 1
	v_bfe_u32 v98, v97, 16, 1
	v_bfe_u32 v99, v96, 16, 1
	v_add3_u32 v91, v91, v102, s76
	v_bfe_u32 v102, v100, 16, 1
	v_add_co_u32_e32 v160, vcc, s56, v148
	v_add3_u32 v96, v96, v99, s76
	v_add3_u32 v97, v97, v98, s76
	v_bfe_u32 v98, v104, 16, 1
	v_bfe_u32 v99, v105, 16, 1
	v_add3_u32 v101, v101, v103, s76
	v_add3_u32 v100, v100, v102, s76
	v_addc_co_u32_e32 v161, vcc, 0, v149, vcc
	v_add3_u32 v105, v105, v99, s76
	v_add3_u32 v104, v104, v98, s76
	v_lshrrev_b32_e32 v98, 16, v100
	v_lshrrev_b32_e32 v99, 16, v101
	global_load_dwordx4 v[100:103], v[160:161], off
	v_bfe_u32 v131, v106, 16, 1
	v_and_or_b32 v98, v96, s77, v98
	v_lshrrev_b32_e32 v96, 16, v104
	s_mov_b64 s[56:57], 0xf000
	v_bfe_u32 v88, v107, 16, 1
	v_add3_u32 v89, v106, v131, s76
	v_and_or_b32 v99, v97, s77, v99
	v_lshrrev_b32_e32 v106, 16, v143
	v_lshrrev_b32_e32 v97, 16, v105
	v_and_or_b32 v96, v90, s77, v96
	v_lshrrev_b32_e32 v90, 16, v141
	v_lshl_add_u64 v[104:105], v[148:149], 0, s[56:57]
	v_add3_u32 v88, v107, v88, s76
	v_and_or_b32 v97, v91, s77, v97
	v_and_or_b32 v91, v129, s77, v90
	v_and_or_b32 v90, v112, s77, v106
	global_load_dwordx4 v[104:107], v[104:105], off offset:16
	v_or_b32_sdwa v92, v92, v135 dst_sel:DWORD dst_unused:UNUSED_PAD src0_sel:DWORD src1_sel:WORD_1
	v_or_b32_sdwa v93, v93, v133 dst_sel:DWORD dst_unused:UNUSED_PAD src0_sel:DWORD src1_sel:WORD_1
	v_or_b32_sdwa v94, v94, v139 dst_sel:DWORD dst_unused:UNUSED_PAD src0_sel:DWORD src1_sel:WORD_1
	v_or_b32_sdwa v95, v95, v137 dst_sel:DWORD dst_unused:UNUSED_PAD src0_sel:DWORD src1_sel:WORD_1
	v_lshrrev_b32_e32 v112, 16, v89
	v_lshrrev_b32_e32 v88, 16, v88
	v_mfma_f32_16x16x32_bf16 v[6:9], v[76:79], v[92:95], v[6:9]
	v_and_or_b32 v89, v75, s77, v88
	v_and_or_b32 v88, v74, s77, v112
	s_mov_b32 s56, 0x1f000
	v_mfma_f32_16x16x32_bf16 v[2:5], v[84:87], v[92:95], v[2:5]
	s_waitcnt vmcnt(1)
	v_mul_f32_e32 v75, 0xbfb8aa3b, v101
	v_mfma_f32_16x16x32_bf16 v[6:9], v[76:79], v[96:99], v[6:9]
	v_exp_f32_e32 v75, v75
	v_mul_f32_e32 v74, 0xbfb8aa3b, v100
	v_exp_f32_e32 v74, v74
	v_mfma_f32_16x16x32_bf16 v[2:5], v[84:87], v[96:99], v[2:5]
	v_add_f32_e32 v75, 1.0, v75
	v_mov_b32_e32 v97, v102
	v_add_f32_e32 v74, 1.0, v74
	v_mfma_f32_16x16x32_bf16 v[6:9], v[80:83], v[92:95], v[6:9]
	v_rcp_f32_e32 v74, v74
	s_waitcnt vmcnt(0)
; __device__ __forceinline__ unsigned f2bf(float f) { unsigned u = __builtin_bit_cast(unsigned, f); return (u + 0x7fffu + ((u >> 16) & 1u)) >> 16; }
; __device__ __forceinline__ f32x4 mfma16(bf16x8 a, bf16x8 b, f32x4 c) { return __builtin_amdgcn_mfma_f32_16x16x32_bf16(a, b, c, 0, 0, 0); }
; __device__ __forceinline__ void phase0(const Args& a, LAS unsigned char* lds, int tid, int wave, int lane, int vcu, int G, int pmask) {
;     ...
;                     for (int bt = 0; bt < 9; ++bt) {
;                         const int b = 16 * bt + i16; const int k = k0 + 32 * ks + 8 * g;
;                         f32x4 c0 = {0.f, 0.f, 0.f, 0.f}, c1 = c0;
;                         if (b < 129) { const float* cr = b == 0 ? cp + k : cs + (size_t)(b - 1) * DM + k; c0 = *(const f32x4*)cr; c1 = *(const f32x4*)(cr + 4); }
;                         unsigned hb[8], lb[8];
; #pragma unroll
;                         for (int j = 0; j < 8; ++j) { const float c = j < 4 ? c0[j & 3] : c1[j & 3]; const float sv = c * __builtin_amdgcn_rcpf(1.f + __expf(-c)); hb[j] = f2bf(sv); lb[j] = f2bf(sv - __uint_as_float(hb[j] << 16)); }
;                         u32x4 wh, wl; wh.x = hb[0] | (hb[1] << 16); wh.y = hb[2] | (hb[3] << 16); wh.z = hb[4] | (hb[5] << 16); wh.w = hb[6] | (hb[7] << 16);
;                         wl.x = lb[0] | (lb[1] << 16); wl.y = lb[2] | (lb[3] << 16); wl.z = lb[4] | (lb[5] << 16); wl.w = lb[6] | (lb[7] << 16);
;                         const bf16x8 bh = __builtin_bit_cast(bf16x8, wh), bl = __builtin_bit_cast(bf16x8, wl);
; #pragma unroll
;                         for (int nt = 0; nt < 2; ++nt) { acc[nt][bt] = mfma16(ah[nt], bh, acc[nt][bt]); acc[nt][bt] = mfma16(ah[nt], bl, acc[nt][bt]); acc[nt][bt] = mfma16(al[nt], bh, acc[nt][bt]); }
	v_mul_f32_e32 v96, 0xbfb8aa3b, v105
	v_mfma_f32_16x16x32_bf16 v[2:5], v[88:91], v[92:95], v[2:5]
	v_mul_f32_e32 v92, 0xbfb8aa3b, v102
	v_exp_f32_e32 v93, v92
	v_rcp_f32_e32 v92, v75
	v_mul_f32_e32 v94, 0xbfb8aa3b, v104
	v_mul_f32_e32 v95, 0xbfb8aa3b, v106
	v_add_f32_e32 v75, 1.0, v93
	v_mul_f32_e32 v93, 0xbfb8aa3b, v103
	v_exp_f32_e32 v93, v93
	v_rcp_f32_e32 v75, v75
	v_exp_f32_e32 v112, v96
	v_mov_b32_e32 v96, v100
	v_add_f32_e32 v93, 1.0, v93
	v_exp_f32_e32 v94, v94
	v_rcp_f32_e32 v93, v93
	v_exp_f32_e32 v95, v95
	v_pk_mul_f32 v[98:99], v[96:97], v[74:75]
	v_add_f32_e32 v94, 1.0, v94
	v_and_b32_sdwa v100, v99, v170 dst_sel:DWORD dst_unused:UNUSED_PAD src0_sel:WORD_1 src1_sel:DWORD
	v_and_b32_sdwa v102, v98, v170 dst_sel:DWORD dst_unused:UNUSED_PAD src0_sel:WORD_1 src1_sel:DWORD
	v_add3_u32 v129, v99, v100, s76
	v_add3_u32 v131, v98, v102, s76
	v_and_b32_e32 v99, 0xffff0000, v129
	v_and_b32_e32 v98, 0xffff0000, v131
	v_mov_b32_e32 v102, v101
	v_add_f32_e32 v95, 1.0, v95
	v_pk_fma_f32 v[74:75], v[96:97], v[74:75], v[98:99] neg_lo:[0,0,1] neg_hi:[0,0,1]
	v_pk_mul_f32 v[96:97], v[102:103], v[92:93]
	v_rcp_f32_e32 v94, v94
	v_rcp_f32_e32 v95, v95
	v_and_b32_sdwa v98, v97, v170 dst_sel:DWORD dst_unused:UNUSED_PAD src0_sel:WORD_1 src1_sel:DWORD
	v_and_b32_sdwa v99, v96, v170 dst_sel:DWORD dst_unused:UNUSED_PAD src0_sel:WORD_1 src1_sel:DWORD
	v_add3_u32 v97, v97, v98, s76
	v_add3_u32 v96, v96, v99, s76
	v_and_b32_e32 v97, 0xffff0000, v97
	v_and_b32_e32 v96, 0xffff0000, v96
	v_pk_fma_f32 v[98:99], v[102:103], v[92:93], v[96:97] neg_lo:[0,0,1] neg_hi:[0,0,1]
	v_mov_b32_e32 v92, v104
	v_mov_b32_e32 v93, v106
	v_pk_mul_f32 v[100:101], v[92:93], v[94:95]
	v_mov_b32_e32 v106, v105
	v_and_b32_sdwa v102, v101, v170 dst_sel:DWORD dst_unused:UNUSED_PAD src0_sel:WORD_1 src1_sel:DWORD
	v_and_b32_sdwa v103, v100, v170 dst_sel:DWORD dst_unused:UNUSED_PAD src0_sel:WORD_1 src1_sel:DWORD
	v_add3_u32 v104, v101, v102, s76
	v_add3_u32 v133, v100, v103, s76
	v_and_b32_e32 v101, 0xffff0000, v104
	v_and_b32_e32 v100, 0xffff0000, v133
	v_pk_fma_f32 v[100:101], v[92:93], v[94:95], v[100:101] neg_lo:[0,0,1] neg_hi:[0,0,1]
	v_mul_f32_e32 v92, 0xbfb8aa3b, v107
	v_exp_f32_e32 v92, v92
	v_add_f32_e32 v93, 1.0, v112
	v_rcp_f32_e32 v94, v93
	v_or_b32_sdwa v93, v97, v129 dst_sel:DWORD dst_unused:UNUSED_PAD src0_sel:DWORD src1_sel:WORD_1
	v_add_f32_e32 v92, 1.0, v92
	v_rcp_f32_e32 v95, v92
	v_or_b32_sdwa v92, v96, v131 dst_sel:DWORD dst_unused:UNUSED_PAD src0_sel:DWORD src1_sel:WORD_1
	v_pk_mul_f32 v[96:97], v[106:107], v[94:95]
	s_nop 0
	v_and_b32_sdwa v102, v97, v170 dst_sel:DWORD dst_unused:UNUSED_PAD src0_sel:WORD_1 src1_sel:DWORD
	v_add3_u32 v97, v97, v102, s76
	v_and_b32_sdwa v102, v96, v170 dst_sel:DWORD dst_unused:UNUSED_PAD src0_sel:WORD_1 src1_sel:DWORD
	v_add3_u32 v96, v96, v102, s76
	v_and_b32_e32 v97, 0xffff0000, v97
	v_and_b32_e32 v96, 0xffff0000, v96
	v_pk_fma_f32 v[102:103], v[106:107], v[94:95], v[96:97] neg_lo:[0,0,1] neg_hi:[0,0,1]
	v_or_b32_sdwa v94, v96, v133 dst_sel:DWORD dst_unused:UNUSED_PAD src0_sel:DWORD src1_sel:WORD_1
	v_or_b32_sdwa v95, v97, v104 dst_sel:DWORD dst_unused:UNUSED_PAD src0_sel:DWORD src1_sel:WORD_1
	v_bfe_u32 v96, v99, 16, 1
	v_bfe_u32 v97, v98, 16, 1
	v_bfe_u32 v104, v103, 16, 1
	v_bfe_u32 v105, v102, 16, 1
	v_add3_u32 v98, v98, v97, s76
	v_add3_u32 v96, v99, v96, s76
	v_add3_u32 v99, v103, v104, s76
	v_bfe_u32 v97, v74, 16, 1
	v_bfe_u32 v103, v75, 16, 1
	v_bfe_u32 v104, v100, 16, 1
	v_add3_u32 v102, v102, v105, s76
	v_bfe_u32 v105, v101, 16, 1
	v_add3_u32 v75, v75, v103, s76
	v_add3_u32 v74, v74, v97, s76
	v_add3_u32 v100, v100, v104, s76
	v_add3_u32 v97, v101, v105, s76
	v_lshrrev_b32_e32 v74, 16, v74
	v_lshrrev_b32_e32 v75, 16, v75
	v_lshrrev_b32_e32 v100, 16, v100
	v_lshrrev_b32_e32 v101, 16, v97
	v_and_or_b32 v97, v96, s77, v75
	v_and_or_b32 v96, v98, s77, v74
	v_and_or_b32 v98, v102, s77, v100
	v_add_co_u32_e32 v102, vcc, s56, v148
	s_mov_b64 s[56:57], 0x1f000
	s_nop 0
	v_addc_co_u32_e32 v103, vcc, 0, v149, vcc
	global_load_dwordx4 v[104:107], v[102:103], off
	v_lshl_add_u64 v[74:75], v[148:149], 0, s[56:57]
	global_load_dwordx4 v[150:153], v[74:75], off offset:16
	v_mfma_f32_16x16x32_bf16 v[50:53], v[76:79], v[92:95], v[50:53]
	v_and_or_b32 v99, v99, s77, v101
	v_add_co_u32_e32 v154, vcc, s78, v148
	v_mfma_f32_16x16x32_bf16 v[54:57], v[84:87], v[92:95], v[54:57]
	s_nop 0
	v_addc_co_u32_e32 v155, vcc, 0, v149, vcc
	v_add_co_u32_e32 v156, vcc, s79, v148
	v_mfma_f32_16x16x32_bf16 v[50:53], v[76:79], v[96:99], v[50:53]
	s_nop 0
	v_addc_co_u32_e32 v157, vcc, 0, v149, vcc
	v_add_co_u32_e32 v162, vcc, s80, v148
	v_mfma_f32_16x16x32_bf16 v[54:57], v[84:87], v[96:99], v[54:57]
	s_nop 0
	v_addc_co_u32_e32 v163, vcc, 0, v149, vcc
	s_waitcnt vmcnt(1)
	v_mul_f32_e32 v75, 0xbfb8aa3b, v105
	v_mfma_f32_16x16x32_bf16 v[50:53], v[80:83], v[92:95], v[50:53]
	v_mul_f32_e32 v74, 0xbfb8aa3b, v104
	v_exp_f32_e32 v75, v75
	v_exp_f32_e32 v74, v74
	v_mfma_f32_16x16x32_bf16 v[54:57], v[88:91], v[92:95], v[54:57]
	v_mul_f32_e32 v92, 0xbfb8aa3b, v106
	v_exp_f32_e32 v93, v92
	v_mul_f32_e32 v92, 0xbfb8aa3b, v107
	v_add_f32_e32 v75, 1.0, v75
	v_exp_f32_e32 v94, v92
	v_add_f32_e32 v74, 1.0, v74
	v_rcp_f32_e32 v92, v75
	v_add_f32_e32 v75, 1.0, v93
	v_rcp_f32_e32 v74, v74
	v_rcp_f32_e32 v75, v75
	v_add_f32_e32 v93, 1.0, v94
	s_waitcnt vmcnt(0)
; __device__ __forceinline__ unsigned f2bf(float f) { unsigned u = __builtin_bit_cast(unsigned, f); return (u + 0x7fffu + ((u >> 16) & 1u)) >> 16; }
; __device__ __forceinline__ f32x4 mfma16(bf16x8 a, bf16x8 b, f32x4 c) { return __builtin_amdgcn_mfma_f32_16x16x32_bf16(a, b, c, 0, 0, 0); }
; __device__ __forceinline__ void phase0(const Args& a, LAS unsigned char* lds, int tid, int wave, int lane, int vcu, int G, int pmask) {
;     ...
;                     for (int bt = 0; bt < 9; ++bt) {
;                         const int b = 16 * bt + i16; const int k = k0 + 32 * ks + 8 * g;
;                         f32x4 c0 = {0.f, 0.f, 0.f, 0.f}, c1 = c0;
;                         if (b < 129) { const float* cr = b == 0 ? cp + k : cs + (size_t)(b - 1) * DM + k; c0 = *(const f32x4*)cr; c1 = *(const f32x4*)(cr + 4); }
;                         unsigned hb[8], lb[8];
; #pragma unroll
;                         for (int j = 0; j < 8; ++j) { const float c = j < 4 ? c0[j & 3] : c1[j & 3]; const float sv = c * __builtin_amdgcn_rcpf(1.f + __expf(-c)); hb[j] = f2bf(sv); lb[j] = f2bf(sv - __uint_as_float(hb[j] << 16)); }
;                         u32x4 wh, wl; wh.x = hb[0] | (hb[1] << 16); wh.y = hb[2] | (hb[3] << 16); wh.z = hb[4] | (hb[5] << 16); wh.w = hb[6] | (hb[7] << 16);
;                         wl.x = lb[0] | (lb[1] << 16); wl.y = lb[2] | (lb[3] << 16); wl.z = lb[4] | (lb[5] << 16); wl.w = lb[6] | (lb[7] << 16);
;                         const bf16x8 bh = __builtin_bit_cast(bf16x8, wh), bl = __builtin_bit_cast(bf16x8, wl);
; #pragma unroll
;                         for (int nt = 0; nt < 2; ++nt) { acc[nt][bt] = mfma16(ah[nt], bh, acc[nt][bt]); acc[nt][bt] = mfma16(ah[nt], bl, acc[nt][bt]); acc[nt][bt] = mfma16(al[nt], bh, acc[nt][bt]); }
	v_mul_f32_e32 v94, 0xbfb8aa3b, v150
	v_exp_f32_e32 v98, v94
	v_mov_b32_e32 v94, v104
	v_mov_b32_e32 v95, v106
	v_rcp_f32_e32 v93, v93
	v_pk_mul_f32 v[96:97], v[94:95], v[74:75]
	v_mov_b32_e32 v106, v105
	v_and_b32_sdwa v99, v97, v170 dst_sel:DWORD dst_unused:UNUSED_PAD src0_sel:WORD_1 src1_sel:DWORD
	v_and_b32_sdwa v100, v96, v170 dst_sel:DWORD dst_unused:UNUSED_PAD src0_sel:WORD_1 src1_sel:DWORD
	v_add3_u32 v112, v97, v99, s76
	v_add3_u32 v129, v96, v100, s76
	v_and_b32_e32 v97, 0xffff0000, v112
	v_and_b32_e32 v96, 0xffff0000, v129
	v_pk_fma_f32 v[74:75], v[94:95], v[74:75], v[96:97] neg_lo:[0,0,1] neg_hi:[0,0,1]
	v_pk_mul_f32 v[94:95], v[106:107], v[92:93]
	s_nop 0
	v_and_b32_sdwa v97, v94, v170 dst_sel:DWORD dst_unused:UNUSED_PAD src0_sel:WORD_1 src1_sel:DWORD
	v_and_b32_sdwa v96, v95, v170 dst_sel:DWORD dst_unused:UNUSED_PAD src0_sel:WORD_1 src1_sel:DWORD
	v_add3_u32 v99, v94, v97, s76
	v_mul_f32_e32 v94, 0xbfb8aa3b, v152
	v_add3_u32 v96, v95, v96, s76
	v_exp_f32_e32 v95, v94
	v_add_f32_e32 v94, 1.0, v98
	v_rcp_f32_e32 v94, v94
	v_and_b32_e32 v97, 0xffff0000, v96
	v_add_f32_e32 v95, 1.0, v95
	v_rcp_f32_e32 v95, v95
	v_and_b32_e32 v96, 0xffff0000, v99
	v_mov_b32_e32 v98, v150
	v_mov_b32_e32 v99, v152
	v_pk_mul_f32 v[100:101], v[98:99], v[94:95]
	v_pk_fma_f32 v[92:93], v[106:107], v[92:93], v[96:97] neg_lo:[0,0,1] neg_hi:[0,0,1]
	v_and_b32_sdwa v104, v101, v170 dst_sel:DWORD dst_unused:UNUSED_PAD src0_sel:WORD_1 src1_sel:DWORD
	v_add3_u32 v106, v101, v104, s76
	v_and_b32_sdwa v101, v100, v170 dst_sel:DWORD dst_unused:UNUSED_PAD src0_sel:WORD_1 src1_sel:DWORD
	v_add3_u32 v107, v100, v101, s76
	v_and_b32_e32 v101, 0xffff0000, v106
	v_and_b32_e32 v100, 0xffff0000, v107
	v_pk_fma_f32 v[94:95], v[98:99], v[94:95], v[100:101] neg_lo:[0,0,1] neg_hi:[0,0,1]
	v_mul_f32_e32 v98, 0xbfb8aa3b, v151
	v_mul_f32_e32 v99, 0xbfb8aa3b, v153
	v_exp_f32_e32 v98, v98
	v_exp_f32_e32 v99, v99
	v_mov_b32_e32 v152, v151
	v_lshl_add_u64 v[150:151], v[146:147], 0, v[124:125]
	v_add_f32_e32 v98, 1.0, v98
	v_add_f32_e32 v99, 1.0, v99
	v_rcp_f32_e32 v98, v98
	v_rcp_f32_e32 v99, v99
	v_or_b32_sdwa v96, v96, v129 dst_sel:DWORD dst_unused:UNUSED_PAD src0_sel:DWORD src1_sel:WORD_1
	v_or_b32_sdwa v97, v97, v112 dst_sel:DWORD dst_unused:UNUSED_PAD src0_sel:DWORD src1_sel:WORD_1
	v_pk_mul_f32 v[100:101], v[152:153], v[98:99]
	s_nop 0
	v_and_b32_sdwa v104, v101, v170 dst_sel:DWORD dst_unused:UNUSED_PAD src0_sel:WORD_1 src1_sel:DWORD
	v_add3_u32 v101, v101, v104, s76
	v_and_b32_sdwa v104, v100, v170 dst_sel:DWORD dst_unused:UNUSED_PAD src0_sel:WORD_1 src1_sel:DWORD
	v_add3_u32 v100, v100, v104, s76
	v_and_b32_e32 v101, 0xffff0000, v101
	v_and_b32_e32 v100, 0xffff0000, v100
	v_pk_fma_f32 v[104:105], v[152:153], v[98:99], v[100:101] neg_lo:[0,0,1] neg_hi:[0,0,1]
	v_or_b32_sdwa v98, v100, v107 dst_sel:DWORD dst_unused:UNUSED_PAD src0_sel:DWORD src1_sel:WORD_1
	v_or_b32_sdwa v99, v101, v106 dst_sel:DWORD dst_unused:UNUSED_PAD src0_sel:DWORD src1_sel:WORD_1
	v_bfe_u32 v100, v93, 16, 1
	v_bfe_u32 v101, v92, 16, 1
	v_bfe_u32 v106, v105, 16, 1
	v_bfe_u32 v107, v104, 16, 1
	v_add3_u32 v92, v92, v101, s76
	v_add3_u32 v93, v93, v100, s76
	v_add3_u32 v100, v104, v107, s76
	v_add3_u32 v101, v105, v106, s76
	v_bfe_u32 v104, v74, 16, 1
	v_bfe_u32 v105, v75, 16, 1
	v_bfe_u32 v106, v94, 16, 1
	v_bfe_u32 v107, v95, 16, 1
	v_add3_u32 v75, v75, v105, s76
	v_add3_u32 v74, v74, v104, s76
	v_add3_u32 v95, v95, v107, s76
	v_add3_u32 v94, v94, v106, s76
	v_lshrrev_b32_e32 v74, 16, v74
	v_lshrrev_b32_e32 v75, 16, v75
	v_lshrrev_b32_e32 v94, 16, v94
	v_lshrrev_b32_e32 v95, 16, v95
	v_and_or_b32 v105, v93, s77, v75
	v_and_or_b32 v104, v92, s77, v74
	v_and_or_b32 v107, v101, s77, v95
	v_and_or_b32 v106, v100, s77, v94
	global_load_dwordx4 v[92:95], v[150:151], off offset:-4096
	v_mfma_f32_16x16x32_bf16 v[66:69], v[76:79], v[96:99], v[66:69]
	v_lshl_add_u64 v[152:153], v[146:147], 0, v[126:127]
	s_waitcnt vmcnt(0)
	v_mul_f32_e32 v75, 0xbfb8aa3b, v93
	v_mfma_f32_16x16x32_bf16 v[70:73], v[84:87], v[96:99], v[70:73]
	v_mul_f32_e32 v74, 0xbfb8aa3b, v92
	v_exp_f32_e32 v75, v75
	v_exp_f32_e32 v74, v74
	v_mfma_f32_16x16x32_bf16 v[66:69], v[76:79], v[104:107], v[66:69]
	v_add_f32_e32 v75, 1.0, v75
	v_add_f32_e32 v74, 1.0, v74
	v_mfma_f32_16x16x32_bf16 v[70:73], v[84:87], v[104:107], v[70:73]
	v_rcp_f32_e32 v74, v74
	v_mfma_f32_16x16x32_bf16 v[66:69], v[80:83], v[96:99], v[66:69]
	v_mfma_f32_16x16x32_bf16 v[70:73], v[88:91], v[96:99], v[70:73]
	v_mul_f32_e32 v96, 0xbfb8aa3b, v94
	v_exp_f32_e32 v97, v96
	v_mul_f32_e32 v96, 0xbfb8aa3b, v95
	v_exp_f32_e32 v98, v96
	v_rcp_f32_e32 v96, v75
	v_add_f32_e32 v75, 1.0, v97
	v_rcp_f32_e32 v75, v75
	v_add_f32_e32 v97, 1.0, v98
	v_rcp_f32_e32 v97, v97
	v_mov_b32_e32 v98, v92
	v_mov_b32_e32 v99, v94
	v_pk_mul_f32 v[100:101], v[98:99], v[74:75]
	s_nop 0
	v_and_b32_sdwa v92, v101, v170 dst_sel:DWORD dst_unused:UNUSED_PAD src0_sel:WORD_1 src1_sel:DWORD
	v_and_b32_sdwa v94, v100, v170 dst_sel:DWORD dst_unused:UNUSED_PAD src0_sel:WORD_1 src1_sel:DWORD
	v_add3_u32 v112, v101, v92, s76
	v_add3_u32 v129, v100, v94, s76
	v_mov_b32_e32 v94, v93
	v_and_b32_e32 v101, 0xffff0000, v112
	v_and_b32_e32 v100, 0xffff0000, v129
	v_pk_mul_f32 v[92:93], v[94:95], v[96:97]
	v_pk_fma_f32 v[74:75], v[98:99], v[74:75], v[100:101] neg_lo:[0,0,1] neg_hi:[0,0,1]
	v_and_b32_sdwa v98, v93, v170 dst_sel:DWORD dst_unused:UNUSED_PAD src0_sel:WORD_1 src1_sel:DWORD
	v_and_b32_sdwa v99, v92, v170 dst_sel:DWORD dst_unused:UNUSED_PAD src0_sel:WORD_1 src1_sel:DWORD
	v_add3_u32 v93, v93, v98, s76
	v_add3_u32 v92, v92, v99, s76
	global_load_dwordx4 v[98:101], v[150:151], off offset:-4080
	v_and_b32_e32 v93, 0xffff0000, v93
	v_and_b32_e32 v92, 0xffff0000, v92
	v_pk_fma_f32 v[96:97], v[94:95], v[96:97], v[92:93] neg_lo:[0,0,1] neg_hi:[0,0,1]
	v_or_b32_sdwa v92, v92, v129 dst_sel:DWORD dst_unused:UNUSED_PAD src0_sel:DWORD src1_sel:WORD_1
	v_or_b32_sdwa v93, v93, v112 dst_sel:DWORD dst_unused:UNUSED_PAD src0_sel:DWORD src1_sel:WORD_1
	s_waitcnt vmcnt(0)
; __device__ __forceinline__ unsigned f2bf(float f) { unsigned u = __builtin_bit_cast(unsigned, f); return (u + 0x7fffu + ((u >> 16) & 1u)) >> 16; }
; __device__ __forceinline__ f32x4 mfma16(bf16x8 a, bf16x8 b, f32x4 c) { return __builtin_amdgcn_mfma_f32_16x16x32_bf16(a, b, c, 0, 0, 0); }
; __device__ __forceinline__ void phase0(const Args& a, LAS unsigned char* lds, int tid, int wave, int lane, int vcu, int G, int pmask) {
;     ...
;                     for (int bt = 0; bt < 9; ++bt) {
;                         const int b = 16 * bt + i16; const int k = k0 + 32 * ks + 8 * g;
;                         f32x4 c0 = {0.f, 0.f, 0.f, 0.f}, c1 = c0;
;                         if (b < 129) { const float* cr = b == 0 ? cp + k : cs + (size_t)(b - 1) * DM + k; c0 = *(const f32x4*)cr; c1 = *(const f32x4*)(cr + 4); }
;                         unsigned hb[8], lb[8];
; #pragma unroll
;                         for (int j = 0; j < 8; ++j) { const float c = j < 4 ? c0[j & 3] : c1[j & 3]; const float sv = c * __builtin_amdgcn_rcpf(1.f + __expf(-c)); hb[j] = f2bf(sv); lb[j] = f2bf(sv - __uint_as_float(hb[j] << 16)); }
;                         u32x4 wh, wl; wh.x = hb[0] | (hb[1] << 16); wh.y = hb[2] | (hb[3] << 16); wh.z = hb[4] | (hb[5] << 16); wh.w = hb[6] | (hb[7] << 16);
;                         wl.x = lb[0] | (lb[1] << 16); wl.y = lb[2] | (lb[3] << 16); wl.z = lb[4] | (lb[5] << 16); wl.w = lb[6] | (lb[7] << 16);
;                         const bf16x8 bh = __builtin_bit_cast(bf16x8, wh), bl = __builtin_bit_cast(bf16x8, wl);
; #pragma unroll
;                         for (int nt = 0; nt < 2; ++nt) { acc[nt][bt] = mfma16(ah[nt], bh, acc[nt][bt]); acc[nt][bt] = mfma16(ah[nt], bl, acc[nt][bt]); acc[nt][bt] = mfma16(al[nt], bh, acc[nt][bt]); }
	v_mul_f32_e32 v104, 0xbfb8aa3b, v98
	v_mul_f32_e32 v94, 0xbfb8aa3b, v100
	v_exp_f32_e32 v104, v104
	v_exp_f32_e32 v95, v94
	v_mov_b32_e32 v105, v100
	v_mov_b32_e32 v100, v99
	v_add_f32_e32 v94, 1.0, v104
	v_add_f32_e32 v95, 1.0, v95
	v_rcp_f32_e32 v94, v94
	v_rcp_f32_e32 v95, v95
	v_mov_b32_e32 v104, v98
	v_pk_mul_f32 v[106:107], v[104:105], v[94:95]
	s_nop 0
	v_and_b32_sdwa v98, v107, v170 dst_sel:DWORD dst_unused:UNUSED_PAD src0_sel:WORD_1 src1_sel:DWORD
	v_add3_u32 v131, v107, v98, s76
	v_and_b32_sdwa v98, v106, v170 dst_sel:DWORD dst_unused:UNUSED_PAD src0_sel:WORD_1 src1_sel:DWORD
	v_add3_u32 v133, v106, v98, s76
	v_and_b32_e32 v107, 0xffff0000, v131
	v_and_b32_e32 v106, 0xffff0000, v133
	v_pk_fma_f32 v[104:105], v[104:105], v[94:95], v[106:107] neg_lo:[0,0,1] neg_hi:[0,0,1]
	v_mul_f32_e32 v94, 0xbfb8aa3b, v99
	v_mul_f32_e32 v95, 0xbfb8aa3b, v101
	v_exp_f32_e32 v94, v94
	v_exp_f32_e32 v95, v95
	v_bfe_u32 v107, v96, 16, 1
	v_add3_u32 v96, v96, v107, s76
	v_add_f32_e32 v94, 1.0, v94
	v_add_f32_e32 v95, 1.0, v95
	v_rcp_f32_e32 v94, v94
	v_rcp_f32_e32 v95, v95
	v_bfe_u32 v107, v105, 16, 1
	v_add3_u32 v105, v105, v107, s76
	v_pk_mul_f32 v[98:99], v[100:101], v[94:95]
	s_nop 0
	v_and_b32_sdwa v106, v99, v170 dst_sel:DWORD dst_unused:UNUSED_PAD src0_sel:WORD_1 src1_sel:DWORD
	v_add3_u32 v99, v99, v106, s76
	v_and_b32_sdwa v106, v98, v170 dst_sel:DWORD dst_unused:UNUSED_PAD src0_sel:WORD_1 src1_sel:DWORD
	v_add3_u32 v98, v98, v106, s76
	v_and_b32_e32 v99, 0xffff0000, v99
	v_and_b32_e32 v98, 0xffff0000, v98
	v_pk_fma_f32 v[100:101], v[100:101], v[94:95], v[98:99] neg_lo:[0,0,1] neg_hi:[0,0,1]
	v_bfe_u32 v106, v97, 16, 1
	v_or_b32_sdwa v94, v98, v133 dst_sel:DWORD dst_unused:UNUSED_PAD src0_sel:DWORD src1_sel:WORD_1
	v_or_b32_sdwa v95, v99, v131 dst_sel:DWORD dst_unused:UNUSED_PAD src0_sel:DWORD src1_sel:WORD_1
	v_bfe_u32 v98, v101, 16, 1
	v_bfe_u32 v99, v100, 16, 1
	v_add3_u32 v97, v97, v106, s76
	v_bfe_u32 v106, v104, 16, 1
	v_add3_u32 v100, v100, v99, s76
	v_add3_u32 v98, v101, v98, s76
	v_bfe_u32 v99, v74, 16, 1
	v_bfe_u32 v101, v75, 16, 1
	v_add3_u32 v104, v104, v106, s76
	v_add3_u32 v75, v75, v101, s76
	v_add3_u32 v74, v74, v99, s76
	v_lshrrev_b32_e32 v101, 16, v104
	v_lshrrev_b32_e32 v99, 16, v105
	global_load_dwordx4 v[104:107], v[154:155], off
	v_mfma_f32_16x16x32_bf16 v[42:45], v[76:79], v[92:95], v[42:45]
	v_lshrrev_b32_e32 v74, 16, v74
	v_lshrrev_b32_e32 v75, 16, v75
	v_and_or_b32 v99, v98, s77, v99
	v_mfma_f32_16x16x32_bf16 v[34:37], v[84:87], v[92:95], v[34:37]
	v_and_or_b32 v98, v100, s77, v101
	v_and_or_b32 v97, v97, s77, v75
	v_and_or_b32 v96, v96, s77, v74
	v_lshl_add_u64 v[74:75], v[148:149], 0, s[28:29]
	s_nop 0
	v_mfma_f32_16x16x32_bf16 v[42:45], v[76:79], v[96:99], v[42:45]
	v_mfma_f32_16x16x32_bf16 v[34:37], v[84:87], v[96:99], v[34:37]
	global_load_dwordx4 v[96:99], v[74:75], off offset:16
	s_waitcnt vmcnt(1)
	v_mul_f32_e32 v74, 0xbfb8aa3b, v104
	v_mul_f32_e32 v75, 0xbfb8aa3b, v106
	v_exp_f32_e32 v74, v74
	v_exp_f32_e32 v75, v75
	v_mfma_f32_16x16x32_bf16 v[42:45], v[80:83], v[92:95], v[42:45]
	v_add_f32_e32 v74, 1.0, v74
	v_add_f32_e32 v75, 1.0, v75
	v_rcp_f32_e32 v74, v74
	v_rcp_f32_e32 v75, v75
	v_mfma_f32_16x16x32_bf16 v[34:37], v[88:91], v[92:95], v[34:37]
	v_mov_b32_e32 v92, v104
	v_mov_b32_e32 v93, v106
	v_pk_mul_f32 v[94:95], v[92:93], v[74:75]
	v_mov_b32_e32 v106, v105
	v_and_b32_sdwa v100, v95, v170 dst_sel:DWORD dst_unused:UNUSED_PAD src0_sel:WORD_1 src1_sel:DWORD
	v_add3_u32 v112, v95, v100, s76
	v_and_b32_sdwa v95, v94, v170 dst_sel:DWORD dst_unused:UNUSED_PAD src0_sel:WORD_1 src1_sel:DWORD
	v_add3_u32 v129, v94, v95, s76
	v_and_b32_e32 v95, 0xffff0000, v112
	v_and_b32_e32 v94, 0xffff0000, v129
	v_pk_fma_f32 v[74:75], v[92:93], v[74:75], v[94:95] neg_lo:[0,0,1] neg_hi:[0,0,1]
	v_mul_f32_e32 v92, 0xbfb8aa3b, v105
	v_mul_f32_e32 v93, 0xbfb8aa3b, v107
	v_exp_f32_e32 v92, v92
	v_exp_f32_e32 v93, v93
	s_waitcnt vmcnt(0)
	v_mov_b32_e32 v104, v96
	v_mov_b32_e32 v105, v98
	v_add_f32_e32 v92, 1.0, v92
	v_add_f32_e32 v93, 1.0, v93
	v_rcp_f32_e32 v92, v92
	v_rcp_f32_e32 v93, v93
	s_nop 0
	v_pk_mul_f32 v[94:95], v[106:107], v[92:93]
	s_nop 0
	v_and_b32_sdwa v100, v95, v170 dst_sel:DWORD dst_unused:UNUSED_PAD src0_sel:WORD_1 src1_sel:DWORD
	v_add3_u32 v95, v95, v100, s76
	v_and_b32_sdwa v100, v94, v170 dst_sel:DWORD dst_unused:UNUSED_PAD src0_sel:WORD_1 src1_sel:DWORD
	v_add3_u32 v94, v94, v100, s76
	v_and_b32_e32 v95, 0xffff0000, v95
	v_and_b32_e32 v94, 0xffff0000, v94
	v_pk_fma_f32 v[100:101], v[106:107], v[92:93], v[94:95] neg_lo:[0,0,1] neg_hi:[0,0,1]
	v_mul_f32_e32 v92, 0xbfb8aa3b, v96
	v_mul_f32_e32 v93, 0xbfb8aa3b, v98
	v_exp_f32_e32 v92, v92
	v_exp_f32_e32 v93, v93
	v_mov_b32_e32 v98, v97
	v_add_f32_e32 v92, 1.0, v92
	v_add_f32_e32 v93, 1.0, v93
	v_rcp_f32_e32 v92, v92
	v_rcp_f32_e32 v93, v93
	s_nop 0
	v_pk_mul_f32 v[106:107], v[104:105], v[92:93]
	s_nop 0
	v_and_b32_sdwa v96, v107, v170 dst_sel:DWORD dst_unused:UNUSED_PAD src0_sel:WORD_1 src1_sel:DWORD
	v_add3_u32 v131, v107, v96, s76
	v_and_b32_sdwa v96, v106, v170 dst_sel:DWORD dst_unused:UNUSED_PAD src0_sel:WORD_1 src1_sel:DWORD
	v_add3_u32 v133, v106, v96, s76
	v_and_b32_e32 v107, 0xffff0000, v131
	v_and_b32_e32 v106, 0xffff0000, v133
	v_pk_fma_f32 v[104:105], v[104:105], v[92:93], v[106:107] neg_lo:[0,0,1] neg_hi:[0,0,1]
	v_mul_f32_e32 v92, 0xbfb8aa3b, v97
	v_mul_f32_e32 v93, 0xbfb8aa3b, v99
	v_exp_f32_e32 v92, v92
	v_exp_f32_e32 v93, v93
	v_add_f32_e32 v92, 1.0, v92
	v_add_f32_e32 v93, 1.0, v93
	v_rcp_f32_e32 v92, v92
	v_rcp_f32_e32 v93, v93
	s_nop 0
	v_pk_mul_f32 v[96:97], v[98:99], v[92:93]
	s_nop 0
	v_and_b32_sdwa v106, v97, v170 dst_sel:DWORD dst_unused:UNUSED_PAD src0_sel:WORD_1 src1_sel:DWORD
; __device__ __forceinline__ unsigned f2bf(float f) { unsigned u = __builtin_bit_cast(unsigned, f); return (u + 0x7fffu + ((u >> 16) & 1u)) >> 16; }
; __device__ __forceinline__ f32x4 mfma16(bf16x8 a, bf16x8 b, f32x4 c) { return __builtin_amdgcn_mfma_f32_16x16x32_bf16(a, b, c, 0, 0, 0); }
; __device__ __forceinline__ void phase0(const Args& a, LAS unsigned char* lds, int tid, int wave, int lane, int vcu, int G, int pmask) {
;     ...
;                     for (int bt = 0; bt < 9; ++bt) {
;                         const int b = 16 * bt + i16; const int k = k0 + 32 * ks + 8 * g;
;                         f32x4 c0 = {0.f, 0.f, 0.f, 0.f}, c1 = c0;
;                         if (b < 129) { const float* cr = b == 0 ? cp + k : cs + (size_t)(b - 1) * DM + k; c0 = *(const f32x4*)cr; c1 = *(const f32x4*)(cr + 4); }
;                         unsigned hb[8], lb[8];
; #pragma unroll
;                         for (int j = 0; j < 8; ++j) { const float c = j < 4 ? c0[j & 3] : c1[j & 3]; const float sv = c * __builtin_amdgcn_rcpf(1.f + __expf(-c)); hb[j] = f2bf(sv); lb[j] = f2bf(sv - __uint_as_float(hb[j] << 16)); }
;                         u32x4 wh, wl; wh.x = hb[0] | (hb[1] << 16); wh.y = hb[2] | (hb[3] << 16); wh.z = hb[4] | (hb[5] << 16); wh.w = hb[6] | (hb[7] << 16);
;                         wl.x = lb[0] | (lb[1] << 16); wl.y = lb[2] | (lb[3] << 16); wl.z = lb[4] | (lb[5] << 16); wl.w = lb[6] | (lb[7] << 16);
;                         const bf16x8 bh = __builtin_bit_cast(bf16x8, wh), bl = __builtin_bit_cast(bf16x8, wl);
; #pragma unroll
;                         for (int nt = 0; nt < 2; ++nt) { acc[nt][bt] = mfma16(ah[nt], bh, acc[nt][bt]); acc[nt][bt] = mfma16(ah[nt], bl, acc[nt][bt]); acc[nt][bt] = mfma16(al[nt], bh, acc[nt][bt]); }
	v_add3_u32 v97, v97, v106, s76
	v_and_b32_sdwa v106, v96, v170 dst_sel:DWORD dst_unused:UNUSED_PAD src0_sel:WORD_1 src1_sel:DWORD
	v_add3_u32 v96, v96, v106, s76
	v_and_b32_e32 v97, 0xffff0000, v97
	v_and_b32_e32 v96, 0xffff0000, v96
	v_pk_fma_f32 v[98:99], v[98:99], v[92:93], v[96:97] neg_lo:[0,0,1] neg_hi:[0,0,1]
	v_or_b32_sdwa v93, v95, v112 dst_sel:DWORD dst_unused:UNUSED_PAD src0_sel:DWORD src1_sel:WORD_1
	v_or_b32_sdwa v95, v97, v131 dst_sel:DWORD dst_unused:UNUSED_PAD src0_sel:DWORD src1_sel:WORD_1
	v_bfe_u32 v97, v100, 16, 1
	v_add3_u32 v100, v100, v97, s76
	v_bfe_u32 v97, v98, 16, 1
	v_add3_u32 v98, v98, v97, s76
	v_bfe_u32 v97, v74, 16, 1
	v_or_b32_sdwa v92, v94, v129 dst_sel:DWORD dst_unused:UNUSED_PAD src0_sel:DWORD src1_sel:WORD_1
	v_or_b32_sdwa v94, v96, v133 dst_sel:DWORD dst_unused:UNUSED_PAD src0_sel:DWORD src1_sel:WORD_1
	v_bfe_u32 v96, v101, 16, 1
	v_bfe_u32 v106, v99, 16, 1
	v_add3_u32 v74, v74, v97, s76
	v_bfe_u32 v97, v105, 16, 1
	v_add3_u32 v96, v101, v96, s76
	v_add3_u32 v99, v99, v106, s76
	v_bfe_u32 v101, v75, 16, 1
	v_bfe_u32 v106, v104, 16, 1
	v_add3_u32 v97, v105, v97, s76
	v_add3_u32 v75, v75, v101, s76
	v_add3_u32 v101, v104, v106, s76
	v_lshrrev_b32_e32 v104, 16, v97
	v_and_or_b32 v99, v99, s77, v104
	global_load_dwordx4 v[104:107], v[156:157], off
	v_mfma_f32_16x16x32_bf16 v[30:33], v[76:79], v[92:95], v[30:33]
	v_lshrrev_b32_e32 v74, 16, v74
	v_lshrrev_b32_e32 v75, 16, v75
	v_lshrrev_b32_e32 v101, 16, v101
	v_mfma_f32_16x16x32_bf16 v[18:21], v[84:87], v[92:95], v[18:21]
	v_and_or_b32 v97, v96, s77, v75
	v_and_or_b32 v96, v100, s77, v74
	v_and_or_b32 v98, v98, s77, v101
	v_lshl_add_u64 v[74:75], v[148:149], 0, s[30:31]
	s_nop 0
	v_mfma_f32_16x16x32_bf16 v[30:33], v[76:79], v[96:99], v[30:33]
	v_mfma_f32_16x16x32_bf16 v[18:21], v[84:87], v[96:99], v[18:21]
	global_load_dwordx4 v[96:99], v[74:75], off offset:16
	s_waitcnt vmcnt(1)
	v_mul_f32_e32 v74, 0xbfb8aa3b, v104
	v_mul_f32_e32 v75, 0xbfb8aa3b, v106
	v_exp_f32_e32 v74, v74
	v_exp_f32_e32 v75, v75
	v_mfma_f32_16x16x32_bf16 v[30:33], v[80:83], v[92:95], v[30:33]
	v_add_f32_e32 v74, 1.0, v74
	v_add_f32_e32 v75, 1.0, v75
	v_rcp_f32_e32 v74, v74
	v_rcp_f32_e32 v75, v75
	v_mfma_f32_16x16x32_bf16 v[18:21], v[88:91], v[92:95], v[18:21]
	v_mov_b32_e32 v92, v104
	v_mov_b32_e32 v93, v106
	v_pk_mul_f32 v[94:95], v[92:93], v[74:75]
	v_mov_b32_e32 v106, v105
	v_and_b32_sdwa v100, v95, v170 dst_sel:DWORD dst_unused:UNUSED_PAD src0_sel:WORD_1 src1_sel:DWORD
	v_add3_u32 v112, v95, v100, s76
	v_and_b32_sdwa v95, v94, v170 dst_sel:DWORD dst_unused:UNUSED_PAD src0_sel:WORD_1 src1_sel:DWORD
	v_add3_u32 v129, v94, v95, s76
	v_and_b32_e32 v95, 0xffff0000, v112
	v_and_b32_e32 v94, 0xffff0000, v129
	v_pk_fma_f32 v[74:75], v[92:93], v[74:75], v[94:95] neg_lo:[0,0,1] neg_hi:[0,0,1]
	v_mul_f32_e32 v92, 0xbfb8aa3b, v105
	v_mul_f32_e32 v93, 0xbfb8aa3b, v107
	v_exp_f32_e32 v92, v92
	v_exp_f32_e32 v93, v93
	s_waitcnt vmcnt(0)
	v_mov_b32_e32 v104, v96
	v_mov_b32_e32 v105, v98
	v_add_f32_e32 v92, 1.0, v92
	v_add_f32_e32 v93, 1.0, v93
	v_rcp_f32_e32 v92, v92
	v_rcp_f32_e32 v93, v93
	s_nop 0
	v_pk_mul_f32 v[94:95], v[106:107], v[92:93]
	s_nop 0
	v_and_b32_sdwa v100, v95, v170 dst_sel:DWORD dst_unused:UNUSED_PAD src0_sel:WORD_1 src1_sel:DWORD
	v_add3_u32 v95, v95, v100, s76
	v_and_b32_sdwa v100, v94, v170 dst_sel:DWORD dst_unused:UNUSED_PAD src0_sel:WORD_1 src1_sel:DWORD
	v_add3_u32 v94, v94, v100, s76
	v_and_b32_e32 v95, 0xffff0000, v95
	v_and_b32_e32 v94, 0xffff0000, v94
	v_pk_fma_f32 v[100:101], v[106:107], v[92:93], v[94:95] neg_lo:[0,0,1] neg_hi:[0,0,1]
	v_mul_f32_e32 v92, 0xbfb8aa3b, v96
	v_mul_f32_e32 v93, 0xbfb8aa3b, v98
	v_exp_f32_e32 v92, v92
	v_exp_f32_e32 v93, v93
	v_mov_b32_e32 v98, v97
	v_add_f32_e32 v92, 1.0, v92
	v_add_f32_e32 v93, 1.0, v93
	v_rcp_f32_e32 v92, v92
	v_rcp_f32_e32 v93, v93
	s_nop 0
	v_pk_mul_f32 v[106:107], v[104:105], v[92:93]
	s_nop 0
	v_and_b32_sdwa v96, v107, v170 dst_sel:DWORD dst_unused:UNUSED_PAD src0_sel:WORD_1 src1_sel:DWORD
	v_add3_u32 v131, v107, v96, s76
	v_and_b32_sdwa v96, v106, v170 dst_sel:DWORD dst_unused:UNUSED_PAD src0_sel:WORD_1 src1_sel:DWORD
	v_add3_u32 v133, v106, v96, s76
	v_and_b32_e32 v107, 0xffff0000, v131
	v_and_b32_e32 v106, 0xffff0000, v133
	v_pk_fma_f32 v[104:105], v[104:105], v[92:93], v[106:107] neg_lo:[0,0,1] neg_hi:[0,0,1]
	v_mul_f32_e32 v92, 0xbfb8aa3b, v97
	v_mul_f32_e32 v93, 0xbfb8aa3b, v99
	v_exp_f32_e32 v92, v92
	v_exp_f32_e32 v93, v93
	v_add_f32_e32 v92, 1.0, v92
	v_add_f32_e32 v93, 1.0, v93
	v_rcp_f32_e32 v92, v92
	v_rcp_f32_e32 v93, v93
	s_nop 0
	v_pk_mul_f32 v[96:97], v[98:99], v[92:93]
	s_nop 0
	v_and_b32_sdwa v106, v97, v170 dst_sel:DWORD dst_unused:UNUSED_PAD src0_sel:WORD_1 src1_sel:DWORD
	v_add3_u32 v97, v97, v106, s76
	v_and_b32_sdwa v106, v96, v170 dst_sel:DWORD dst_unused:UNUSED_PAD src0_sel:WORD_1 src1_sel:DWORD
	v_add3_u32 v96, v96, v106, s76
	v_and_b32_e32 v97, 0xffff0000, v97
	v_and_b32_e32 v96, 0xffff0000, v96
	v_pk_fma_f32 v[98:99], v[98:99], v[92:93], v[96:97] neg_lo:[0,0,1] neg_hi:[0,0,1]
	v_or_b32_sdwa v92, v94, v129 dst_sel:DWORD dst_unused:UNUSED_PAD src0_sel:DWORD src1_sel:WORD_1
	v_or_b32_sdwa v94, v96, v133 dst_sel:DWORD dst_unused:UNUSED_PAD src0_sel:DWORD src1_sel:WORD_1
	v_bfe_u32 v96, v100, 16, 1
	v_add3_u32 v96, v100, v96, s76
	v_bfe_u32 v100, v98, 16, 1
	v_add3_u32 v98, v98, v100, s76
	v_bfe_u32 v100, v99, 16, 1
	v_add3_u32 v99, v99, v100, s76
	v_bfe_u32 v100, v75, 16, 1
	v_or_b32_sdwa v93, v95, v112 dst_sel:DWORD dst_unused:UNUSED_PAD src0_sel:DWORD src1_sel:WORD_1
	v_or_b32_sdwa v95, v97, v131 dst_sel:DWORD dst_unused:UNUSED_PAD src0_sel:DWORD src1_sel:WORD_1
	v_bfe_u32 v97, v101, 16, 1
	v_add3_u32 v75, v75, v100, s76
	v_bfe_u32 v100, v74, 16, 1
	v_add3_u32 v97, v101, v97, s76
	v_add3_u32 v74, v74, v100, s76
	v_bfe_u32 v100, v105, 16, 1
	v_bfe_u32 v101, v104, 16, 1
	v_mfma_f32_16x16x32_bf16 v[62:65], v[76:79], v[92:95], v[62:65]
	v_add3_u32 v100, v105, v100, s76
	v_add3_u32 v101, v104, v101, s76
	v_lshrrev_b32_e32 v74, 16, v74
	v_mfma_f32_16x16x32_bf16 v[46:49], v[84:87], v[92:95], v[46:49]
	v_lshrrev_b32_e32 v75, 16, v75
	v_and_or_b32 v97, v97, s77, v75
	v_and_or_b32 v96, v96, s77, v74
	v_lshrrev_b32_e32 v74, 16, v101
	v_lshrrev_b32_e32 v75, 16, v100
	v_and_or_b32 v99, v99, s77, v75
	v_and_or_b32 v98, v98, s77, v74
	v_lshl_add_u64 v[74:75], v[148:149], 0, s[34:35]
	s_nop 0
	v_mfma_f32_16x16x32_bf16 v[62:65], v[76:79], v[96:99], v[62:65]
	v_mfma_f32_16x16x32_bf16 v[46:49], v[84:87], v[96:99], v[46:49]
	global_load_dwordx4 v[96:99], v[162:163], off
	v_mfma_f32_16x16x32_bf16 v[62:65], v[80:83], v[92:95], v[62:65]
	v_mfma_f32_16x16x32_bf16 v[46:49], v[88:91], v[92:95], v[46:49]
	global_load_dwordx4 v[92:95], v[74:75], off offset:16
	s_waitcnt vmcnt(1)
; __device__ __forceinline__ unsigned f2bf(float f) { unsigned u = __builtin_bit_cast(unsigned, f); return (u + 0x7fffu + ((u >> 16) & 1u)) >> 16; }
; __device__ __forceinline__ f32x4 mfma16(bf16x8 a, bf16x8 b, f32x4 c) { return __builtin_amdgcn_mfma_f32_16x16x32_bf16(a, b, c, 0, 0, 0); }
; __device__ __forceinline__ void phase0(const Args& a, LAS unsigned char* lds, int tid, int wave, int lane, int vcu, int G, int pmask) {
;     ...
;                     for (int bt = 0; bt < 9; ++bt) {
;                         const int b = 16 * bt + i16; const int k = k0 + 32 * ks + 8 * g;
;                         f32x4 c0 = {0.f, 0.f, 0.f, 0.f}, c1 = c0;
;                         if (b < 129) { const float* cr = b == 0 ? cp + k : cs + (size_t)(b - 1) * DM + k; c0 = *(const f32x4*)cr; c1 = *(const f32x4*)(cr + 4); }
;                         unsigned hb[8], lb[8];
; #pragma unroll
;                         for (int j = 0; j < 8; ++j) { const float c = j < 4 ? c0[j & 3] : c1[j & 3]; const float sv = c * __builtin_amdgcn_rcpf(1.f + __expf(-c)); hb[j] = f2bf(sv); lb[j] = f2bf(sv - __uint_as_float(hb[j] << 16)); }
;                         u32x4 wh, wl; wh.x = hb[0] | (hb[1] << 16); wh.y = hb[2] | (hb[3] << 16); wh.z = hb[4] | (hb[5] << 16); wh.w = hb[6] | (hb[7] << 16);
;                         wl.x = lb[0] | (lb[1] << 16); wl.y = lb[2] | (lb[3] << 16); wl.z = lb[4] | (lb[5] << 16); wl.w = lb[6] | (lb[7] << 16);
;                         const bf16x8 bh = __builtin_bit_cast(bf16x8, wh), bl = __builtin_bit_cast(bf16x8, wl);
; #pragma unroll
;                         for (int nt = 0; nt < 2; ++nt) { acc[nt][bt] = mfma16(ah[nt], bh, acc[nt][bt]); acc[nt][bt] = mfma16(ah[nt], bl, acc[nt][bt]); acc[nt][bt] = mfma16(al[nt], bh, acc[nt][bt]); }
	v_mul_f32_e32 v74, 0xbfb8aa3b, v96
	v_mul_f32_e32 v75, 0xbfb8aa3b, v98
	v_exp_f32_e32 v74, v74
	v_exp_f32_e32 v75, v75
	v_mov_b32_e32 v100, v96
	v_mov_b32_e32 v101, v98
	v_add_f32_e32 v74, 1.0, v74
	v_add_f32_e32 v75, 1.0, v75
	v_rcp_f32_e32 v74, v74
	v_rcp_f32_e32 v75, v75
	v_mul_f32_e32 v98, 0xbfb8aa3b, v99
	v_exp_f32_e32 v98, v98
	v_pk_mul_f32 v[104:105], v[100:101], v[74:75]
	s_nop 0
	v_and_b32_sdwa v96, v105, v170 dst_sel:DWORD dst_unused:UNUSED_PAD src0_sel:WORD_1 src1_sel:DWORD
	v_add3_u32 v112, v105, v96, s76
	v_and_b32_sdwa v96, v104, v170 dst_sel:DWORD dst_unused:UNUSED_PAD src0_sel:WORD_1 src1_sel:DWORD
	v_add3_u32 v129, v104, v96, s76
	v_mul_f32_e32 v96, 0xbfb8aa3b, v97
	v_exp_f32_e32 v96, v96
	v_and_b32_e32 v105, 0xffff0000, v112
	v_and_b32_e32 v104, 0xffff0000, v129
	v_add_f32_e32 v98, 1.0, v98
	v_add_f32_e32 v96, 1.0, v96
	v_pk_fma_f32 v[74:75], v[100:101], v[74:75], v[104:105] neg_lo:[0,0,1] neg_hi:[0,0,1]
	v_rcp_f32_e32 v100, v96
	v_rcp_f32_e32 v101, v98
	v_mov_b32_e32 v98, v97
	s_waitcnt vmcnt(0)
	v_mov_b32_e32 v105, v94
	v_pk_mul_f32 v[96:97], v[98:99], v[100:101]
	s_nop 0
	v_and_b32_sdwa v104, v97, v170 dst_sel:DWORD dst_unused:UNUSED_PAD src0_sel:WORD_1 src1_sel:DWORD
	v_add3_u32 v97, v97, v104, s76
	v_and_b32_sdwa v104, v96, v170 dst_sel:DWORD dst_unused:UNUSED_PAD src0_sel:WORD_1 src1_sel:DWORD
	v_add3_u32 v96, v96, v104, s76
	v_and_b32_e32 v97, 0xffff0000, v97
	v_and_b32_e32 v96, 0xffff0000, v96
	v_pk_fma_f32 v[98:99], v[98:99], v[100:101], v[96:97] neg_lo:[0,0,1] neg_hi:[0,0,1]
	v_mul_f32_e32 v100, 0xbfb8aa3b, v92
	v_mul_f32_e32 v101, 0xbfb8aa3b, v94
	v_exp_f32_e32 v100, v100
	v_exp_f32_e32 v101, v101
	v_mov_b32_e32 v104, v92
	v_mul_f32_e32 v94, 0xbfb8aa3b, v95
	v_add_f32_e32 v100, 1.0, v100
	v_add_f32_e32 v101, 1.0, v101
	v_rcp_f32_e32 v100, v100
	v_rcp_f32_e32 v101, v101
	v_exp_f32_e32 v94, v94
	v_pk_mul_f32 v[106:107], v[104:105], v[100:101]
	s_nop 0
	v_and_b32_sdwa v92, v107, v170 dst_sel:DWORD dst_unused:UNUSED_PAD src0_sel:WORD_1 src1_sel:DWORD
	v_add3_u32 v131, v107, v92, s76
	v_and_b32_sdwa v92, v106, v170 dst_sel:DWORD dst_unused:UNUSED_PAD src0_sel:WORD_1 src1_sel:DWORD
	v_add3_u32 v133, v106, v92, s76
	v_mul_f32_e32 v92, 0xbfb8aa3b, v93
	v_exp_f32_e32 v92, v92
	v_and_b32_e32 v107, 0xffff0000, v131
	v_and_b32_e32 v106, 0xffff0000, v133
	v_add_f32_e32 v94, 1.0, v94
	v_add_f32_e32 v92, 1.0, v92
	v_pk_fma_f32 v[100:101], v[104:105], v[100:101], v[106:107] neg_lo:[0,0,1] neg_hi:[0,0,1]
	v_rcp_f32_e32 v104, v92
	v_rcp_f32_e32 v105, v94
	v_mov_b32_e32 v94, v93
	v_pk_mul_f32 v[92:93], v[94:95], v[104:105]
	s_nop 0
	v_and_b32_sdwa v106, v93, v170 dst_sel:DWORD dst_unused:UNUSED_PAD src0_sel:WORD_1 src1_sel:DWORD
	v_add3_u32 v93, v93, v106, s76
	v_and_b32_sdwa v106, v92, v170 dst_sel:DWORD dst_unused:UNUSED_PAD src0_sel:WORD_1 src1_sel:DWORD
	v_add3_u32 v92, v92, v106, s76
	v_and_b32_e32 v107, 0xffff0000, v93
	v_and_b32_e32 v106, 0xffff0000, v92
	v_pk_fma_f32 v[104:105], v[94:95], v[104:105], v[106:107] neg_lo:[0,0,1] neg_hi:[0,0,1]
	v_or_b32_sdwa v92, v96, v129 dst_sel:DWORD dst_unused:UNUSED_PAD src0_sel:DWORD src1_sel:WORD_1
	v_bfe_u32 v96, v98, 16, 1
	v_add3_u32 v96, v98, v96, s76
	v_bfe_u32 v98, v104, 16, 1
	v_add3_u32 v98, v104, v98, s76
	v_bfe_u32 v104, v75, 16, 1
	v_add3_u32 v75, v75, v104, s76
	v_bfe_u32 v104, v74, 16, 1
	v_or_b32_sdwa v93, v97, v112 dst_sel:DWORD dst_unused:UNUSED_PAD src0_sel:DWORD src1_sel:WORD_1
	v_or_b32_sdwa v94, v106, v133 dst_sel:DWORD dst_unused:UNUSED_PAD src0_sel:DWORD src1_sel:WORD_1
	v_or_b32_sdwa v95, v107, v131 dst_sel:DWORD dst_unused:UNUSED_PAD src0_sel:DWORD src1_sel:WORD_1
	v_bfe_u32 v97, v99, 16, 1
	v_add3_u32 v74, v74, v104, s76
	v_bfe_u32 v104, v101, 16, 1
	v_add3_u32 v97, v99, v97, s76
	v_bfe_u32 v99, v105, 16, 1
	v_add3_u32 v101, v101, v104, s76
	v_bfe_u32 v104, v100, 16, 1
	v_lshrrev_b32_e32 v74, 16, v74
	v_mfma_f32_16x16x32_bf16 v[58:61], v[76:79], v[92:95], v[58:61]
	v_add3_u32 v99, v105, v99, s76
	v_add3_u32 v100, v100, v104, s76
	v_and_or_b32 v96, v96, s77, v74
	v_mfma_f32_16x16x32_bf16 v[38:41], v[84:87], v[92:95], v[38:41]
	v_lshrrev_b32_e32 v74, 16, v101
	v_lshrrev_b32_e32 v75, 16, v75
	v_and_or_b32 v99, v99, s77, v74
	v_lshrrev_b32_e32 v74, 16, v100
	v_and_or_b32 v97, v97, s77, v75
	v_and_or_b32 v98, v98, s77, v74
	s_nop 1
	v_mfma_f32_16x16x32_bf16 v[58:61], v[76:79], v[96:99], v[58:61]
	v_mfma_f32_16x16x32_bf16 v[38:41], v[84:87], v[96:99], v[38:41]
	global_load_dwordx4 v[96:99], v[152:153], off offset:-4096
	s_waitcnt vmcnt(0)
; __device__ __forceinline__ unsigned f2bf(float f) { unsigned u = __builtin_bit_cast(unsigned, f); return (u + 0x7fffu + ((u >> 16) & 1u)) >> 16; }
; __device__ __forceinline__ f32x4 mfma16(bf16x8 a, bf16x8 b, f32x4 c) { return __builtin_amdgcn_mfma_f32_16x16x32_bf16(a, b, c, 0, 0, 0); }
; __device__ __forceinline__ void phase0(const Args& a, LAS unsigned char* lds, int tid, int wave, int lane, int vcu, int G, int pmask) {
;     ...
;                     for (int bt = 0; bt < 9; ++bt) {
;                         const int b = 16 * bt + i16; const int k = k0 + 32 * ks + 8 * g;
;                         f32x4 c0 = {0.f, 0.f, 0.f, 0.f}, c1 = c0;
;                         if (b < 129) { const float* cr = b == 0 ? cp + k : cs + (size_t)(b - 1) * DM + k; c0 = *(const f32x4*)cr; c1 = *(const f32x4*)(cr + 4); }
;                         unsigned hb[8], lb[8];
; #pragma unroll
;                         for (int j = 0; j < 8; ++j) { const float c = j < 4 ? c0[j & 3] : c1[j & 3]; const float sv = c * __builtin_amdgcn_rcpf(1.f + __expf(-c)); hb[j] = f2bf(sv); lb[j] = f2bf(sv - __uint_as_float(hb[j] << 16)); }
;                         u32x4 wh, wl; wh.x = hb[0] | (hb[1] << 16); wh.y = hb[2] | (hb[3] << 16); wh.z = hb[4] | (hb[5] << 16); wh.w = hb[6] | (hb[7] << 16);
;                         wl.x = lb[0] | (lb[1] << 16); wl.y = lb[2] | (lb[3] << 16); wl.z = lb[4] | (lb[5] << 16); wl.w = lb[6] | (lb[7] << 16);
;                         const bf16x8 bh = __builtin_bit_cast(bf16x8, wh), bl = __builtin_bit_cast(bf16x8, wl);
; #pragma unroll
;                         for (int nt = 0; nt < 2; ++nt) { acc[nt][bt] = mfma16(ah[nt], bh, acc[nt][bt]); acc[nt][bt] = mfma16(ah[nt], bl, acc[nt][bt]); acc[nt][bt] = mfma16(al[nt], bh, acc[nt][bt]); }
	v_mul_f32_e32 v74, 0xbfb8aa3b, v96
	v_mul_f32_e32 v75, 0xbfb8aa3b, v98
	v_exp_f32_e32 v74, v74
	v_exp_f32_e32 v75, v75
	v_mfma_f32_16x16x32_bf16 v[58:61], v[80:83], v[92:95], v[58:61]
	v_add_f32_e32 v74, 1.0, v74
	v_add_f32_e32 v75, 1.0, v75
	v_rcp_f32_e32 v74, v74
	v_rcp_f32_e32 v75, v75
	v_mfma_f32_16x16x32_bf16 v[38:41], v[88:91], v[92:95], v[38:41]
	v_mov_b32_e32 v92, v96
	v_mov_b32_e32 v93, v98
	v_pk_mul_f32 v[94:95], v[92:93], v[74:75]
	v_mov_b32_e32 v98, v97
	v_and_b32_sdwa v96, v95, v170 dst_sel:DWORD dst_unused:UNUSED_PAD src0_sel:WORD_1 src1_sel:DWORD
	v_add3_u32 v112, v95, v96, s76
	v_and_b32_sdwa v95, v94, v170 dst_sel:DWORD dst_unused:UNUSED_PAD src0_sel:WORD_1 src1_sel:DWORD
	v_add3_u32 v129, v94, v95, s76
	v_and_b32_e32 v95, 0xffff0000, v112
	v_and_b32_e32 v94, 0xffff0000, v129
	v_pk_fma_f32 v[74:75], v[92:93], v[74:75], v[94:95] neg_lo:[0,0,1] neg_hi:[0,0,1]
	v_mul_f32_e32 v92, 0xbfb8aa3b, v97
	v_mul_f32_e32 v93, 0xbfb8aa3b, v99
	v_exp_f32_e32 v92, v92
	v_exp_f32_e32 v93, v93
	v_add_f32_e32 v92, 1.0, v92
	v_add_f32_e32 v93, 1.0, v93
	v_rcp_f32_e32 v92, v92
	v_rcp_f32_e32 v93, v93
	s_nop 0
	v_pk_mul_f32 v[94:95], v[98:99], v[92:93]
	s_nop 0
	v_and_b32_sdwa v96, v95, v170 dst_sel:DWORD dst_unused:UNUSED_PAD src0_sel:WORD_1 src1_sel:DWORD
	v_add3_u32 v95, v95, v96, s76
	v_and_b32_sdwa v96, v94, v170 dst_sel:DWORD dst_unused:UNUSED_PAD src0_sel:WORD_1 src1_sel:DWORD
	v_add3_u32 v94, v94, v96, s76
	v_and_b32_e32 v95, 0xffff0000, v95
	v_and_b32_e32 v94, 0xffff0000, v94
	v_pk_fma_f32 v[92:93], v[98:99], v[92:93], v[94:95] neg_lo:[0,0,1] neg_hi:[0,0,1]
	global_load_dwordx4 v[96:99], v[152:153], off offset:-4080
	v_or_b32_sdwa v94, v94, v129 dst_sel:DWORD dst_unused:UNUSED_PAD src0_sel:DWORD src1_sel:WORD_1
	v_or_b32_sdwa v95, v95, v112 dst_sel:DWORD dst_unused:UNUSED_PAD src0_sel:DWORD src1_sel:WORD_1
	s_waitcnt vmcnt(0)
	v_mul_f32_e32 v100, 0xbfb8aa3b, v96
	v_mul_f32_e32 v101, 0xbfb8aa3b, v98
	v_exp_f32_e32 v100, v100
	v_exp_f32_e32 v101, v101
	v_mov_b32_e32 v104, v96
	v_mov_b32_e32 v105, v98
	v_add_f32_e32 v100, 1.0, v100
	v_add_f32_e32 v101, 1.0, v101
	v_rcp_f32_e32 v100, v100
	v_rcp_f32_e32 v101, v101
	v_mul_f32_e32 v98, 0xbfb8aa3b, v99
	v_exp_f32_e32 v98, v98
	v_pk_mul_f32 v[106:107], v[104:105], v[100:101]
	s_nop 0
	v_and_b32_sdwa v96, v107, v170 dst_sel:DWORD dst_unused:UNUSED_PAD src0_sel:WORD_1 src1_sel:DWORD
	v_add3_u32 v131, v107, v96, s76
	v_and_b32_sdwa v96, v106, v170 dst_sel:DWORD dst_unused:UNUSED_PAD src0_sel:WORD_1 src1_sel:DWORD
	v_add3_u32 v133, v106, v96, s76
	v_mul_f32_e32 v96, 0xbfb8aa3b, v97
	v_exp_f32_e32 v96, v96
	v_and_b32_e32 v107, 0xffff0000, v131
	v_and_b32_e32 v106, 0xffff0000, v133
	v_add_f32_e32 v98, 1.0, v98
	v_add_f32_e32 v96, 1.0, v96
	v_pk_fma_f32 v[100:101], v[104:105], v[100:101], v[106:107] neg_lo:[0,0,1] neg_hi:[0,0,1]
	v_rcp_f32_e32 v104, v96
	v_rcp_f32_e32 v105, v98
	v_mov_b32_e32 v98, v97
	v_pk_mul_f32 v[96:97], v[98:99], v[104:105]
	s_nop 0
	v_and_b32_sdwa v106, v97, v170 dst_sel:DWORD dst_unused:UNUSED_PAD src0_sel:WORD_1 src1_sel:DWORD
	v_add3_u32 v97, v97, v106, s76
	v_and_b32_sdwa v106, v96, v170 dst_sel:DWORD dst_unused:UNUSED_PAD src0_sel:WORD_1 src1_sel:DWORD
	v_add3_u32 v96, v96, v106, s76
	v_and_b32_e32 v97, 0xffff0000, v97
	v_and_b32_e32 v96, 0xffff0000, v96
	v_pk_fma_f32 v[98:99], v[98:99], v[104:105], v[96:97] neg_lo:[0,0,1] neg_hi:[0,0,1]
	v_bfe_u32 v104, v92, 16, 1
	v_add3_u32 v92, v92, v104, s76
	v_bfe_u32 v104, v93, 16, 1
	v_add3_u32 v93, v93, v104, s76
	v_bfe_u32 v104, v98, 16, 1
	v_add3_u32 v98, v98, v104, s76
	v_bfe_u32 v104, v99, 16, 1
	v_add3_u32 v99, v99, v104, s76
	v_bfe_u32 v104, v101, 16, 1
	v_add3_u32 v101, v101, v104, s76
	v_bfe_u32 v104, v100, 16, 1
	v_or_b32_sdwa v96, v96, v133 dst_sel:DWORD dst_unused:UNUSED_PAD src0_sel:DWORD src1_sel:WORD_1
	v_or_b32_sdwa v97, v97, v131 dst_sel:DWORD dst_unused:UNUSED_PAD src0_sel:DWORD src1_sel:WORD_1
	v_add3_u32 v100, v100, v104, s76
	v_bfe_u32 v104, v75, 16, 1
	v_add3_u32 v75, v75, v104, s76
	v_bfe_u32 v104, v74, 16, 1
	v_mfma_f32_16x16x32_bf16 v[26:29], v[76:79], v[94:97], v[26:29]
	v_add3_u32 v74, v74, v104, s76
	v_lshrrev_b32_e32 v100, 16, v100
	v_lshrrev_b32_e32 v101, 16, v101
	v_mfma_f32_16x16x32_bf16 v[14:17], v[84:87], v[94:97], v[14:17]
	v_lshrrev_b32_e32 v75, 16, v75
	v_lshrrev_b32_e32 v74, 16, v74
	v_and_or_b32 v101, v99, s77, v101
	v_and_or_b32 v100, v98, s77, v100
	v_and_or_b32 v99, v93, s77, v75
	v_and_or_b32 v98, v92, s77, v74
	v_mov_b32_e32 v92, 0
	v_mov_b32_e32 v93, 0
	v_mfma_f32_16x16x32_bf16 v[26:29], v[76:79], v[98:101], v[26:29]
	v_mov_b32_e32 v74, 0
	v_mfma_f32_16x16x32_bf16 v[14:17], v[84:87], v[98:101], v[14:17]
	v_mov_b32_e32 v100, 0
	v_mov_b32_e32 v101, 0
	v_mfma_f32_16x16x32_bf16 v[26:29], v[80:83], v[94:97], v[26:29]
	v_mfma_f32_16x16x32_bf16 v[14:17], v[88:91], v[94:97], v[14:17]
	v_mov_b32_e32 v96, 0
	v_mov_b32_e32 v97, 0
	v_mov_b32_e32 v94, 0
	v_mov_b32_e32 v95, 0
	s_and_saveexec_b64 s[56:57], s[2:3]
	s_cbranch_execz .LBB0_18
	v_add_co_u32_e32 v96, vcc, 0x7f000, v146
	v_lshl_add_u64 v[92:93], v[146:147], 0, s[36:37]
	s_nop 0
	v_addc_co_u32_e32 v97, vcc, 0, v147, vcc
	global_load_dwordx4 v[92:95], v[92:93], off offset:16
	s_nop 0
	global_load_dwordx4 v[96:99], v[96:97], off
	s_waitcnt vmcnt(1)
	v_mov_b32_e32 v100, v93
	v_mov_b32_e32 v93, v94
	v_mov_b32_e32 v101, v95
	s_waitcnt vmcnt(0)
	v_mov_b32_e32 v94, v97
	v_mov_b32_e32 v97, v98
	v_mov_b32_e32 v95, v99

; #define LAS __attribute__((address_space(3)))
; __device__ __forceinline__ void phase5(const Args& a, LAS unsigned char* lds, int tid, int wave, int lane, int vcu, int G, int pmode) {
;     ...
;         const int c = u >> 2, hd = u & 3, tg = wave, tl = 16 * tg + i16; const size_t t = (size_t)128 * c + tl;
;         __syncthreads();
;         if (!(pmode & 2)) for (int x = tid; x < 3 * 128 * 16; x += NTHREADS) {
;             const int mat = x >> 11, row = (x >> 4) & 127, ch = x & 15;
;             const bf16* src = mat == 0 ? P1 + ((size_t)128 * c + row) * P1W + C_MK + hd * 128 + 8 * ch
;                             : mat == 1 ? PT + (size_t)(R_MVT + hd * 128 + row) * MT + 128 * c + 8 * ch
;                                        : CPREV + ((size_t)(c * 4 + hd) * 128 + row) * 128 + 8 * ch;
;             *(LAS u32x4*)(lds + mat * 34816 + row * 272 + 16 * ch) = *(const u32x4*)src;
;         }
;         if (tid < 128) LB[tid] = BS[((size_t)128 * c + tid) * 4 + hd];
;         const float mprev = MPREV[c * 4 + hd], bmax = fmaxf(mprev, CMB[t * 4 + hd]), aint = __expf(mprev - bmax), m_t = (IG[t * 4 + hd] - BS[t * 4 + hd]) + bmax;
;         bf16x8 qf[4];
; #pragma unroll
;         for (int ks = 0; ks < 4; ++ks) qf[ks] = ldfrag(P1 + t * P1W + C_MQ + hd * 128 + 32 * ks + 8 * g);
;         u32x2 mo[8];
; #pragma unroll
;         for (int d = 0; d < 8; ++d) mo[d] = *(const u32x2*)(P1 + t * P1W + C_MO + hd * 128 + 16 * d + 4 * g);
;         __syncthreads();
;         f32x4 an[8], ac[8];
; #pragma unroll
;         for (int d = 0; d < 8; ++d) { an[d] = (f32x4){0.f, 0.f, 0.f, 0.f}; ac[d] = an[d]; }
.LBB0_1064:
	s_and_b32 s4, s54, 3
	s_ashr_i32 s41, s40, 31
	s_lshl_b32 s10, s4, 8
	s_ashr_i32 s4, s40, 2
	s_lshl_b64 s[6:7], s[40:41], 15
	s_lshl_b32 s8, s4, 7
	s_waitcnt lgkmcnt(0)
	v_lshl_add_u64 v[2:3], v[142:143], 0, s[6:7]
	s_mul_i32 s6, s4, 0xa0000
	s_and_b32 s30, s40, 3
	s_ashr_i32 s9, s8, 31
	s_mul_hi_i32 s7, s4, 0xa0000
	s_or_b32 s6, s6, s10
	s_ashr_i32 s5, s4, 31
	s_lshl_b32 s12, s30, 7
	v_lshl_add_u64 v[4:5], s[8:9], 1, v[144:145]
	v_lshl_add_u64 v[6:7], v[154:155], 0, s[6:7]
	v_mul_u32_u24_e32 v48, 0x110, v149
	v_add_u32_e32 v49, s12, v149
	global_load_dwordx4 v[8:11], v[6:7], off
	v_lshl_add_u64 v[180:181], v[6:7], 0, s[36:37]
	global_load_dwordx4 v[12:15], v[180:181], off
	v_lshl_add_u64 v[180:181], v[180:181], 0, s[36:37]
	global_load_dwordx4 v[16:19], v[180:181], off
	v_lshl_add_u64 v[180:181], v[180:181], 0, s[36:37]
	global_load_dwordx4 v[20:23], v[180:181], off
	v_mad_u64_u32 v[180:181], s[8:9], v49, s48, v[4:5]
	s_mov_b64 s[10:11], 0x110000
	global_load_dwordx4 v[24:27], v[180:181], off
	v_lshl_add_u64 v[180:181], v[180:181], 0, s[10:11]
	global_load_dwordx4 v[28:31], v[180:181], off
	v_lshl_add_u64 v[180:181], v[180:181], 0, s[10:11]
	global_load_dwordx4 v[32:35], v[180:181], off
	v_lshl_add_u64 v[180:181], v[180:181], 0, s[10:11]
	global_load_dwordx4 v[36:39], v[180:181], off
	v_lshlrev_b32_e32 v134, 8, v149
	s_mov_b64 s[10:11], 0x2000
	v_lshl_add_u64 v[180:181], v[2:3], 0, v[134:135]
	global_load_dwordx4 v[40:43], v[180:181], off
	v_lshl_add_u64 v[180:181], v[180:181], 0, s[10:11]
	global_load_dwordx4 v[44:47], v[180:181], off
	v_lshl_add_u64 v[180:181], v[180:181], 0, s[10:11]
	global_load_dwordx4 v[172:175], v[180:181], off
	v_lshl_add_u64 v[180:181], v[180:181], 0, s[10:11]
	global_load_dwordx4 v[176:179], v[180:181], off
	v_add_u32_e32 v48, v48, v138
	v_add_u32_e32 v49, 0x8800, v48
	s_barrier
.LBB0_1072:
	v_mov_b64_e32 v[2:3], s[30:31]
	s_and_saveexec_b64 s[6:7], s[0:1]
	s_xor_b64 s[6:7], exec, s[6:7]
	v_mov_b64_e32 v[2:3], s[30:31]
	s_or_saveexec_b64 s[6:7], s[6:7]
	s_lshl_b64 s[42:43], s[4:5], 7
	s_xor_b64 exec, exec, s[6:7]
	s_cbranch_execz .LBB0_1076
	v_mov_b32_e32 v5, s43
	v_or_b32_e32 v4, s42, v0
	v_lshl_add_u64 v[4:5], v[4:5], 4, s[22:23]
	s_lshl_b32 s30, s30, 2
	v_lshl_add_u64 v[4:5], v[4:5], 0, s[30:31]
	global_load_dword v4, v[4:5], off
	s_waitcnt vmcnt(0)
	ds_write_b32 v131, v4
.LBB0_1076:
	s_or_b64 exec, exec, s[6:7]
	s_waitcnt vmcnt(0)
	ds_write_b128 v48, v[8:11]
	ds_write_b128 v48, v[12:15] offset:8704
	ds_write_b128 v48, v[16:19] offset:17408
	ds_write_b128 v48, v[20:23] offset:26112
	ds_write_b128 v48, v[24:27] offset:34816
	ds_write_b128 v48, v[28:31] offset:43520
	ds_write_b128 v48, v[32:35] offset:52224
	ds_write_b128 v48, v[36:39] offset:60928
	ds_write_b128 v49, v[40:43] offset:34816
	ds_write_b128 v49, v[44:47] offset:43520
	ds_write_b128 v49, v[172:175] offset:52224
	ds_write_b128 v49, v[176:179] offset:60928
	s_lshl_b64 s[4:5], s[40:41], 2
	s_add_u32 s4, s33, s4
	v_lshl_add_u64 v[4:5], s[42:43], 0, v[132:133]
	s_addc_u32 s5, s44, s5
	v_mov_b64_e32 v[10:11], s[20:21]
	global_load_dword v134, v135, s[4:5]
	v_lshlrev_b64 v[6:7], 2, v[4:5]
	v_mad_u64_u32 v[10:11], s[4:5], v4, s46, v[10:11]
	v_or_b32_e32 v163, v3, v7
	v_or_b32_e32 v162, v2, v6
	v_mad_i32_i24 v11, v5, s46, v11
	s_lshl_b32 s30, s12, 1
	v_lshlrev_b64 v[2:3], 2, v[162:163]
	v_lshl_add_u64 v[14:15], v[10:11], 0, s[30:31]
	v_mov_b32_e32 v159, v135
	v_lshl_add_u64 v[6:7], s[24:25], 0, v[2:3]
	v_lshl_add_u64 v[8:9], s[26:27], 0, v[2:3]
	v_lshl_add_u64 v[2:3], s[22:23], 0, v[2:3]
	v_lshl_add_u64 v[16:17], v[14:15], 0, v[158:159]
	v_mov_b32_e32 v161, v135
	global_load_dword v49, v[6:7], off
	global_load_dword v159, v[8:9], off
	global_load_dword v195, v[2:3], off
	s_nop 0
	global_load_dwordx4 v[2:5], v[16:17], off offset:2048
	global_load_dwordx4 v[6:9], v[16:17], off offset:2112
	global_load_dwordx4 v[10:13], v[16:17], off offset:2176
	v_lshl_add_u64 v[18:19], v[14:15], 0, v[160:161]
	global_load_dwordx4 v[14:17], v[16:17], off offset:2240
	s_nop 0
	global_load_dwordx2 v[182:183], v[18:19], off offset:3072
	global_load_dwordx2 v[180:181], v[18:19], off offset:3104
	global_load_dwordx2 v[178:179], v[18:19], off offset:3136
	global_load_dwordx2 v[176:177], v[18:19], off offset:3168
	global_load_dwordx2 v[174:175], v[18:19], off offset:3200
	global_load_dwordx2 v[172:173], v[18:19], off offset:3232
	global_load_dwordx2 v[170:171], v[18:19], off offset:3264
	global_load_dwordx2 v[164:165], v[18:19], off offset:3296
	v_mov_b32_e32 v184, 0
	s_mov_b64 s[4:5], 15
	v_mov_b64_e32 v[186:187], v[156:157]
	v_mov_b32_e32 v185, v167
	v_mov_b32_e32 v196, v153
	v_mov_b32_e32 v197, v151
	v_mov_b32_e32 v18, 0
	v_mov_b32_e32 v22, 0
	v_mov_b32_e32 v26, 0
	v_mov_b32_e32 v30, 0
	v_mov_b32_e32 v34, 0
	v_mov_b32_e32 v38, 0
	v_mov_b32_e32 v42, 0
	v_mov_b32_e32 v46, 0
	v_mov_b32_e32 v19, v184
	v_mov_b32_e32 v20, v184
	v_mov_b32_e32 v21, v184
	v_mov_b32_e32 v23, v184
	v_mov_b32_e32 v24, v184
	v_mov_b32_e32 v25, v184
	v_mov_b32_e32 v27, v184
	v_mov_b32_e32 v28, v184
	v_mov_b32_e32 v29, v184
	v_mov_b32_e32 v31, v184
	v_mov_b32_e32 v32, v184
	v_mov_b32_e32 v33, v184
	v_mov_b32_e32 v35, v184
	v_mov_b32_e32 v36, v184
	v_mov_b32_e32 v37, v184
	v_mov_b32_e32 v39, v184
	v_mov_b32_e32 v40, v184
	v_mov_b32_e32 v41, v184
	v_mov_b32_e32 v43, v184
	v_mov_b32_e32 v44, v184
	v_mov_b32_e32 v45, v184
	v_mov_b32_e32 v47, v184
	v_mov_b32_e32 v48, v184
	s_waitcnt lgkmcnt(0)
	s_barrier
; #define LAS __attribute__((address_space(3)))
; __device__ __forceinline__ float bf_lo(unsigned w) { return __uint_as_float(w << 16); }
; __device__ __forceinline__ float bf_hi(unsigned w) { return __uint_as_float(w & 0xffff0000u); }
; __device__ __forceinline__ f32x4 mfma16(bf16x8 a, bf16x8 b, f32x4 c) { return __builtin_amdgcn_mfma_f32_16x16x32_bf16(a, b, c, 0, 0, 0); }
; __device__ __forceinline__ void phase5(const Args& a, LAS unsigned char* lds, int tid, int wave, int lane, int vcu, int G, int pmode) {
;     ...
;         const float mprev = MPREV[c * 4 + hd], bmax = fmaxf(mprev, CMB[t * 4 + hd]), aint = __expf(mprev - bmax), m_t = (IG[t * 4 + hd] - BS[t * 4 + hd]) + bmax;
;     ...
; #pragma unroll 2
;         for (int ks = 0; ks < ((pmode & 4) ? 0 : 4); ++ks) {
; #pragma unroll
;             for (int d = 0; d < 8; ++d) ac[d] = mfma16(*(const LAS bf16x8*)(LC + (16 * d + i16) * 272 + 64 * ks + 16 * g), qf[ks], ac[d]);
;             const u32x4 qw = __builtin_bit_cast(u32x4, qf[ks]); const float* np = NPREV + (size_t)(c * 4 + hd) * 128 + 32 * ks + 8 * g;
;             const f32x4 n0 = *(const f32x4*)np, n1 = *(const f32x4*)(np + 4);
;             nq += (bf_lo(qw.x) * n0[0] + bf_hi(qw.x) * n0[1]) + (bf_lo(qw.y) * n0[2] + bf_hi(qw.y) * n0[3]) + (bf_lo(qw.z) * n1[0] + bf_hi(qw.z) * n1[1]) + (bf_lo(qw.w) * n1[2] + bf_hi(qw.w) * n1[3]);
;         }
	s_waitcnt vmcnt(15)
	v_max_f32_e32 v50, v134, v134
	s_waitcnt vmcnt(14)
	v_max_f32_e32 v49, v49, v49
	v_max_f32_e32 v161, v50, v49
	v_mov_b32_e32 v49, v184
	v_add_u32_e32 v114, v185, v137
	v_add_u32_e32 v114, 0x11000, v114
	global_load_dwordx4 v[50:53], v[186:187], off offset:-128
	global_load_dwordx4 v[54:57], v[186:187], off offset:-112
	global_load_dwordx4 v[58:61], v[186:187], off
	global_load_dwordx4 v[62:65], v[186:187], off offset:16
	global_load_dwordx4 v[66:69], v[186:187], off offset:128
	global_load_dwordx4 v[70:73], v[186:187], off offset:144
	global_load_dwordx4 v[74:77], v[186:187], off offset:256
	global_load_dwordx4 v[78:81], v[186:187], off offset:272
	ds_read_b128 v[82:85], v114
	ds_read_b128 v[86:89], v114 offset:4352
	ds_read_b128 v[90:93], v114 offset:8704
	ds_read_b128 v[94:97], v114 offset:13056
	ds_read_b128 v[98:101], v114 offset:17408
	ds_read_b128 v[102:105], v114 offset:21760
	ds_read_b128 v[106:109], v114 offset:26112
	ds_read_b128 v[110:113], v114 offset:30464
	ds_read_b128 v[198:201], v114 offset:64
	ds_read_b128 v[202:205], v114 offset:4416
	ds_read_b128 v[206:209], v114 offset:8768
	ds_read_b128 v[210:213], v114 offset:13120
	ds_read_b128 v[214:217], v114 offset:17472
	ds_read_b128 v[218:221], v114 offset:21824
	ds_read_b128 v[222:225], v114 offset:26176
	ds_read_b128 v[226:229], v114 offset:30528
	s_waitcnt vmcnt(16)
	s_waitcnt lgkmcnt(8)
	v_mfma_f32_16x16x32_bf16 v[46:49], v[82:85], v[2:5], v[46:49]
	v_mfma_f32_16x16x32_bf16 v[42:45], v[86:89], v[2:5], v[42:45]
	v_mfma_f32_16x16x32_bf16 v[38:41], v[90:93], v[2:5], v[38:41]
	v_mfma_f32_16x16x32_bf16 v[34:37], v[94:97], v[2:5], v[34:37]
	v_mfma_f32_16x16x32_bf16 v[30:33], v[98:101], v[2:5], v[30:33]
	v_mfma_f32_16x16x32_bf16 v[26:29], v[102:105], v[2:5], v[26:29]
	v_mfma_f32_16x16x32_bf16 v[22:25], v[106:109], v[2:5], v[22:25]
	v_mfma_f32_16x16x32_bf16 v[18:21], v[110:113], v[2:5], v[18:21]
	ds_read_b128 v[82:85], v114 offset:128
	ds_read_b128 v[86:89], v114 offset:4480
	ds_read_b128 v[90:93], v114 offset:8832
	ds_read_b128 v[94:97], v114 offset:13184
	ds_read_b128 v[98:101], v114 offset:17536
	ds_read_b128 v[102:105], v114 offset:21888
	ds_read_b128 v[106:109], v114 offset:26240
	ds_read_b128 v[110:113], v114 offset:30592
	s_waitcnt lgkmcnt(8)
	v_mfma_f32_16x16x32_bf16 v[46:49], v[198:201], v[6:9], v[46:49]
	v_mfma_f32_16x16x32_bf16 v[42:45], v[202:205], v[6:9], v[42:45]
	v_mfma_f32_16x16x32_bf16 v[38:41], v[206:209], v[6:9], v[38:41]
	v_mfma_f32_16x16x32_bf16 v[34:37], v[210:213], v[6:9], v[34:37]
	v_mfma_f32_16x16x32_bf16 v[30:33], v[214:217], v[6:9], v[30:33]
	v_mfma_f32_16x16x32_bf16 v[26:29], v[218:221], v[6:9], v[26:29]
	v_mfma_f32_16x16x32_bf16 v[22:25], v[222:225], v[6:9], v[22:25]
	v_mfma_f32_16x16x32_bf16 v[18:21], v[226:229], v[6:9], v[18:21]
	ds_read_b128 v[198:201], v114 offset:192
	ds_read_b128 v[202:205], v114 offset:4544
	ds_read_b128 v[206:209], v114 offset:8896
	ds_read_b128 v[210:213], v114 offset:13248
	ds_read_b128 v[214:217], v114 offset:17600
	ds_read_b128 v[218:221], v114 offset:21952
	ds_read_b128 v[222:225], v114 offset:26304
	ds_read_b128 v[226:229], v114 offset:30656
	s_waitcnt lgkmcnt(8)
	v_mfma_f32_16x16x32_bf16 v[46:49], v[82:85], v[10:13], v[46:49]
	v_mfma_f32_16x16x32_bf16 v[42:45], v[86:89], v[10:13], v[42:45]
	v_mfma_f32_16x16x32_bf16 v[38:41], v[90:93], v[10:13], v[38:41]
	v_mfma_f32_16x16x32_bf16 v[34:37], v[94:97], v[10:13], v[34:37]
	v_mfma_f32_16x16x32_bf16 v[30:33], v[98:101], v[10:13], v[30:33]
	v_mfma_f32_16x16x32_bf16 v[26:29], v[102:105], v[10:13], v[26:29]
	v_mfma_f32_16x16x32_bf16 v[22:25], v[106:109], v[10:13], v[22:25]
	v_mfma_f32_16x16x32_bf16 v[18:21], v[110:113], v[10:13], v[18:21]
	s_waitcnt lgkmcnt(0)
; #define LAS __attribute__((address_space(3)))
; __device__ __forceinline__ float bf_lo(unsigned w) { return __uint_as_float(w << 16); }
; __device__ __forceinline__ float bf_hi(unsigned w) { return __uint_as_float(w & 0xffff0000u); }
; __device__ __forceinline__ f32x4 mfma16(bf16x8 a, bf16x8 b, f32x4 c) { return __builtin_amdgcn_mfma_f32_16x16x32_bf16(a, b, c, 0, 0, 0); }
; __device__ __forceinline__ void phase5(const Args& a, LAS unsigned char* lds, int tid, int wave, int lane, int vcu, int G, int pmode) {
;     ...
;         for (int ks = 0; ks < ((pmode & 4) ? 0 : 4); ++ks) {
; #pragma unroll
;             for (int d = 0; d < 8; ++d) ac[d] = mfma16(*(const LAS bf16x8*)(LC + (16 * d + i16) * 272 + 64 * ks + 16 * g), qf[ks], ac[d]);
;             const u32x4 qw = __builtin_bit_cast(u32x4, qf[ks]); const float* np = NPREV + (size_t)(c * 4 + hd) * 128 + 32 * ks + 8 * g;
;             const f32x4 n0 = *(const f32x4*)np, n1 = *(const f32x4*)(np + 4);
;             nq += (bf_lo(qw.x) * n0[0] + bf_hi(qw.x) * n0[1]) + (bf_lo(qw.y) * n0[2] + bf_hi(qw.y) * n0[3]) + (bf_lo(qw.z) * n1[0] + bf_hi(qw.z) * n1[1]) + (bf_lo(qw.w) * n1[2] + bf_hi(qw.w) * n1[3]);
;         }
;         float dsum = 0.f;
	v_mfma_f32_16x16x32_bf16 v[46:49], v[198:201], v[14:17], v[46:49]
	v_mfma_f32_16x16x32_bf16 v[42:45], v[202:205], v[14:17], v[42:45]
	v_mfma_f32_16x16x32_bf16 v[38:41], v[206:209], v[14:17], v[38:41]
	v_mfma_f32_16x16x32_bf16 v[34:37], v[210:213], v[14:17], v[34:37]
	v_mfma_f32_16x16x32_bf16 v[30:33], v[214:217], v[14:17], v[30:33]
	v_mfma_f32_16x16x32_bf16 v[26:29], v[218:221], v[14:17], v[26:29]
	v_mfma_f32_16x16x32_bf16 v[22:25], v[222:225], v[14:17], v[22:25]
	v_mfma_f32_16x16x32_bf16 v[18:21], v[226:229], v[14:17], v[18:21]
	s_waitcnt vmcnt(0)
	v_lshlrev_b32_e32 v115, 16, v2
	v_and_b32_e32 v119, 0xffff0000, v2
	v_mul_f32_e32 v115, v115, v50
	v_fmac_f32_e32 v115, v119, v51
	v_lshlrev_b32_e32 v116, 16, v3
	v_and_b32_e32 v119, 0xffff0000, v3
	v_mul_f32_e32 v116, v116, v52
	v_fmac_f32_e32 v116, v119, v53
	v_lshlrev_b32_e32 v117, 16, v4
	v_and_b32_e32 v119, 0xffff0000, v4
	v_mul_f32_e32 v117, v117, v54
	v_fmac_f32_e32 v117, v119, v55
	v_lshlrev_b32_e32 v118, 16, v5
	v_and_b32_e32 v119, 0xffff0000, v5
	v_mul_f32_e32 v118, v118, v56
	v_fmac_f32_e32 v118, v119, v57
	v_add_f32_e32 v115, v115, v116
	v_add_f32_e32 v115, v115, v117
	v_add_f32_e32 v115, v115, v118
	v_add_f32_e32 v184, v184, v115
	v_lshlrev_b32_e32 v115, 16, v6
	v_and_b32_e32 v119, 0xffff0000, v6
	v_mul_f32_e32 v115, v115, v58
	v_fmac_f32_e32 v115, v119, v59
	v_lshlrev_b32_e32 v116, 16, v7
	v_and_b32_e32 v119, 0xffff0000, v7
	v_mul_f32_e32 v116, v116, v60
	v_fmac_f32_e32 v116, v119, v61
	v_lshlrev_b32_e32 v117, 16, v8
	v_and_b32_e32 v119, 0xffff0000, v8
	v_mul_f32_e32 v117, v117, v62
	v_fmac_f32_e32 v117, v119, v63
	v_lshlrev_b32_e32 v118, 16, v9
	v_and_b32_e32 v119, 0xffff0000, v9
	v_mul_f32_e32 v118, v118, v64
	v_fmac_f32_e32 v118, v119, v65
	v_add_f32_e32 v115, v115, v116
	v_add_f32_e32 v115, v115, v117
	v_add_f32_e32 v115, v115, v118
	v_add_f32_e32 v184, v184, v115
	v_lshlrev_b32_e32 v115, 16, v10
	v_and_b32_e32 v119, 0xffff0000, v10
	v_mul_f32_e32 v115, v115, v66
	v_fmac_f32_e32 v115, v119, v67
	v_lshlrev_b32_e32 v116, 16, v11
	v_and_b32_e32 v119, 0xffff0000, v11
	v_mul_f32_e32 v116, v116, v68
	v_fmac_f32_e32 v116, v119, v69
	v_lshlrev_b32_e32 v117, 16, v12
	v_and_b32_e32 v119, 0xffff0000, v12
	v_mul_f32_e32 v117, v117, v70
	v_fmac_f32_e32 v117, v119, v71
	v_lshlrev_b32_e32 v118, 16, v13
	v_and_b32_e32 v119, 0xffff0000, v13
	v_mul_f32_e32 v118, v118, v72
	v_fmac_f32_e32 v118, v119, v73
	v_add_f32_e32 v115, v115, v116
	v_add_f32_e32 v115, v115, v117
	v_add_f32_e32 v115, v115, v118
	v_add_f32_e32 v184, v184, v115
	v_lshlrev_b32_e32 v115, 16, v14
	v_and_b32_e32 v119, 0xffff0000, v14
	v_mul_f32_e32 v115, v115, v74
	v_fmac_f32_e32 v115, v119, v75
	v_lshlrev_b32_e32 v116, 16, v15
	v_and_b32_e32 v119, 0xffff0000, v15
	v_mul_f32_e32 v116, v116, v76
	v_fmac_f32_e32 v116, v119, v77
	v_lshlrev_b32_e32 v117, 16, v16
	v_and_b32_e32 v119, 0xffff0000, v16
	v_mul_f32_e32 v117, v117, v78
	v_fmac_f32_e32 v117, v119, v79
	v_lshlrev_b32_e32 v118, 16, v17
	v_and_b32_e32 v119, 0xffff0000, v17
	v_mul_f32_e32 v118, v118, v80
	v_fmac_f32_e32 v118, v119, v81
	v_add_f32_e32 v115, v115, v116
	v_add_f32_e32 v115, v115, v117
	v_add_f32_e32 v115, v115, v118
	v_add_f32_e32 v184, v184, v115
	v_mov_b32_e32 v185, 0
	v_mov_b32_e32 v82, v191
	v_mov_b32_e32 v83, v136
	v_mov_b32_e32 v84, v190
	v_mov_b32_e32 v85, v189
	v_mov_b32_e32 v86, v188
	v_mov_b32_e32 v87, v169
	s_mov_b32 s41, s47
	v_mov_b32_e32 v50, v185
	v_mov_b32_e32 v51, v185
	v_mov_b32_e32 v52, v185
	v_mov_b32_e32 v53, v185
	v_mov_b32_e32 v54, v185
	v_mov_b32_e32 v55, v185
	v_mov_b32_e32 v56, v185
	v_mov_b32_e32 v57, v185
	v_mov_b32_e32 v58, v185
	v_mov_b32_e32 v59, v185
	v_mov_b32_e32 v60, v185
	v_mov_b32_e32 v61, v185
	v_mov_b32_e32 v62, v185
	v_mov_b32_e32 v63, v185
	v_mov_b32_e32 v64, v185
	v_mov_b32_e32 v65, v185
	v_mov_b32_e32 v66, v185
	v_mov_b32_e32 v67, v185
	v_mov_b32_e32 v68, v185
	v_mov_b32_e32 v69, v185
	v_mov_b32_e32 v70, v185
	v_mov_b32_e32 v71, v185
	v_mov_b32_e32 v72, v185
	v_mov_b32_e32 v73, v185
	v_mov_b32_e32 v74, v185
	v_mov_b32_e32 v75, v185
	v_mov_b32_e32 v76, v185
	v_mov_b32_e32 v77, v185
	v_mov_b32_e32 v78, v185
	v_mov_b32_e32 v79, v185
	v_mov_b32_e32 v80, v185
	v_mov_b32_e32 v81, v185
